# residual GEMM epilogues (G2,G5,G7,G9): the 64 xlane_add hops (lane^16, lane^32) via v_permlane16/32_swap instead of ds_bpermute; counted lgkmcnt waits there made lgkmcnt(0); same operands
# speedup vs baseline: 1.0014x; 1.0014x over previous
; __device__ __forceinline__ unsigned cvt_pk_bf16(float lo, float hi) { unsigned r; asm volatile("v_cvt_pk_bf16_f32 %0, %1, %2" : "=v"(r) : "v"(lo), "v"(hi)); return r; }
; __device__ __forceinline__ float xlane_add(float v, int lane_, int mask) { return v + __uint_as_float((unsigned)__builtin_amdgcn_ds_bpermute((lane_ ^ mask) << 2, (int)__float_as_uint(v))); }
;     __device__ __forceinline__ void operator()(const f32x4 (&acc)[2][2][4][2], const Unit& u, int wr, int wc, int fr, int fq) const {
;     ...
;         for (int ai = 0; ai < 2; ++ai) { u32x4 xa[4][2];
; #pragma unroll
;             for (int m = 0; m < 4; ++m)
; #pragma unroll
;                 for (int bj = 0; bj < 2; ++bj) xa[m][bj] = *(const __attribute__((address_space(1))) u32x4*)(S + (size_t)(row0 + ai * HALF + m * 16) * ldx + col0 + bj * HALF);
; #pragma unroll
;             for (int m = 0; m < 4; ++m) { float ss = 0.f; const int row = row0 + ai * HALF + m * 16;
; #pragma unroll
;                 for (int bj = 0; bj < 2; ++bj) { const u32x4 xw = xa[m][bj]; const f32x4 a0 = acc[ai][bj][m][0], a1 = acc[ai][bj][m][1];
;                     const float v0 = __uint_as_float(xw.x << 16) + a0[0] * alpha, v1 = __uint_as_float(xw.x & 0xffff0000u) + a0[1] * alpha, v2 = __uint_as_float(xw.y << 16) + a0[2] * alpha, v3 = __uint_as_float(xw.y & 0xffff0000u) + a0[3] * alpha;
;                     const float v4 = __uint_as_float(xw.z << 16) + a1[0] * alpha, v5 = __uint_as_float(xw.z & 0xffff0000u) + a1[1] * alpha, v6 = __uint_as_float(xw.w << 16) + a1[2] * alpha, v7 = __uint_as_float(xw.w & 0xffff0000u) + a1[3] * alpha;
;                     u32x4 w; w.x = cvt_pk_bf16(v0, v1); w.y = cvt_pk_bf16(v2, v3); w.z = cvt_pk_bf16(v4, v5); w.w = cvt_pk_bf16(v6, v7);
;                     *(__attribute__((address_space(1))) u32x4*)(D + (size_t)row * ldx + col0 + bj * HALF) = w;
;                     ss += (v0 * v0 + v1 * v1) + (v2 * v2 + v3 * v3) + (v4 * v4 + v5 * v5) + (v6 * v6 + v7 * v7); }
;                 ss = xlane_add(ss, lane_, 16); ss = xlane_add(ss, lane_, 32);
;                 if (fq == 0) ((__attribute__((address_space(1))) float*)ssq)[(size_t)slot * mrows + row] = ss; }
.LBB0_289:
	v_lshl_or_b32 v168, s85, 8, v182
	v_lshl_add_u32 v166, s86, 8, v180
	v_ashrrev_i32_e32 v169, 31, v168
	v_lshlrev_b64 v[190:191], 1, v[168:169]
	v_ashrrev_i32_e32 v167, 31, v166
	v_lshl_add_u64 v[170:171], s[52:53], 0, v[190:191]
	v_lshlrev_b64 v[172:173], 12, v[166:167]
	v_lshl_add_u64 v[120:121], v[170:171], 0, v[172:173]
	global_load_dwordx4 v[186:189], v[120:121], off
	global_load_dwordx4 v[152:155], v[120:121], off offset:256
	v_or_b32_e32 v178, 16, v166
	v_ashrrev_i32_e32 v179, 31, v178
	v_lshlrev_b64 v[120:121], 12, v[178:179]
	v_or_b32_e32 v176, 32, v166
	v_lshl_add_u64 v[120:121], v[170:171], 0, v[120:121]
	v_ashrrev_i32_e32 v177, 31, v176
	global_load_dwordx4 v[148:151], v[120:121], off
	global_load_dwordx4 v[144:147], v[120:121], off offset:256
	v_lshlrev_b64 v[120:121], 12, v[176:177]
	v_or_b32_e32 v174, 48, v166
	v_lshl_add_u64 v[120:121], v[170:171], 0, v[120:121]
	v_ashrrev_i32_e32 v175, 31, v174
	global_load_dwordx4 v[140:143], v[120:121], off
	global_load_dwordx4 v[136:139], v[120:121], off offset:256
	v_lshlrev_b64 v[120:121], 12, v[174:175]
	v_lshl_add_u64 v[120:121], v[170:171], 0, v[120:121]
	global_load_dwordx4 v[132:135], v[120:121], off
	s_nop 0
	global_load_dwordx4 v[120:123], v[120:121], off offset:256
	s_lshl_b32 s38, s85, 2
	s_or_b32 s61, s38, s76
	s_mul_hi_i32 s60, s61, 0x28000
	s_mul_i32 s61, s61, 0x28000
	s_waitcnt vmcnt(0)
	v_lshlrev_b32_e32 v193, 16, v187
	v_lshlrev_b32_e32 v192, 16, v186
	v_and_b32_e32 v186, 0xffff0000, v186
	v_fmac_f32_e32 v193, 0.5, v130
	v_and_b32_e32 v130, 0xffff0000, v187
	v_fmac_f32_e32 v192, 0.5, v128
	v_fmac_f32_e32 v186, 0.5, v129
	v_fmac_f32_e32 v130, 0.5, v131
	v_lshlrev_b32_e32 v131, 16, v188
	v_and_b32_e32 v187, 0xffff0000, v188
	v_lshl_add_u64 v[128:129], s[52:53], 0, v[172:173]
	v_fmac_f32_e32 v131, 0.5, v124
	v_fmac_f32_e32 v187, 0.5, v125
	v_lshlrev_b32_e32 v188, 16, v189
	v_and_b32_e32 v189, 0xffff0000, v189
	v_cvt_pk_bf16_f32 v124, v192, v186
	v_cvt_pk_bf16_f32 v125, v193, v130
	v_lshl_add_u64 v[128:129], v[128:129], 0, v[190:191]
	v_fmac_f32_e32 v188, 0.5, v126
	v_fmac_f32_e32 v189, 0.5, v127
	v_cvt_pk_bf16_f32 v126, v131, v187
	v_cvt_pk_bf16_f32 v127, v188, v189
	global_store_dwordx4 v[128:129], v[124:127], off
	s_nop 1
	v_mul_f32_e32 v124, v186, v186
	v_mul_f32_e32 v125, v130, v130
	v_fmac_f32_e32 v124, v192, v192
	v_fmac_f32_e32 v125, v193, v193
	v_add_f32_e32 v124, v124, v125
	v_mul_f32_e32 v125, v187, v187
	v_fmac_f32_e32 v125, v131, v131
	v_add_f32_e32 v124, v125, v124
	v_mul_f32_e32 v125, v189, v189
	v_fmac_f32_e32 v125, v188, v188
	v_add_f32_e32 v124, v125, v124
	v_lshlrev_b32_e32 v125, 16, v152
	v_fmac_f32_e32 v125, 0.5, v116
	v_and_b32_e32 v116, 0xffff0000, v152
	v_fmac_f32_e32 v116, 0.5, v117
	v_lshlrev_b32_e32 v117, 16, v153
	v_fmac_f32_e32 v117, 0.5, v118
	v_and_b32_e32 v118, 0xffff0000, v153
	v_fmac_f32_e32 v118, 0.5, v119
	v_lshlrev_b32_e32 v119, 16, v154
	v_and_b32_e32 v126, 0xffff0000, v154
	v_fmac_f32_e32 v119, 0.5, v112
	v_fmac_f32_e32 v126, 0.5, v113
	v_lshlrev_b32_e32 v127, 16, v155
	v_and_b32_e32 v130, 0xffff0000, v155
	v_cvt_pk_bf16_f32 v112, v125, v116
	v_cvt_pk_bf16_f32 v113, v117, v118
	v_fmac_f32_e32 v127, 0.5, v114
	v_fmac_f32_e32 v130, 0.5, v115
	v_cvt_pk_bf16_f32 v114, v119, v126
	v_cvt_pk_bf16_f32 v115, v127, v130
	global_store_dwordx4 v[128:129], v[112:115], off offset:256
	s_nop 1
	v_mul_f32_e32 v112, v116, v116
	v_mul_f32_e32 v113, v118, v118
	v_fmac_f32_e32 v112, v125, v125
	v_fmac_f32_e32 v113, v117, v117
	v_add_f32_e32 v112, v112, v113
	v_mul_f32_e32 v113, v126, v126
	v_fmac_f32_e32 v113, v119, v119
	v_add_f32_e32 v112, v113, v112
	v_mul_f32_e32 v113, v130, v130
	v_fmac_f32_e32 v113, v127, v127
	v_add_f32_e32 v112, v113, v112
	v_add_f32_e32 v112, v124, v112
	v_mov_b32_e32 v113, v112
	s_nop 1
	v_permlane16_swap_b32_e32 v113, v112
	s_waitcnt lgkmcnt(0)
	v_add_f32_e32 v112, v112, v113
	v_mov_b32_e32 v113, v112
	s_nop 1
	v_permlane32_swap_b32_e32 v113, v112
	s_and_saveexec_b64 s[58:59], s[42:43]
	s_cbranch_execz .LBB0_291
	s_add_u32 s38, s74, s61
	s_addc_u32 s39, s75, s60
	s_waitcnt lgkmcnt(0)
	v_add_f32_e32 v114, v112, v113
	v_lshl_add_u64 v[112:113], v[166:167], 2, s[38:39]
	global_store_dword v[112:113], v114, off
.LBB0_291:
	s_or_b64 exec, exec, s[58:59]
	v_lshlrev_b32_e32 v114, 16, v148
	v_fmac_f32_e32 v114, 0.5, v108
	v_and_b32_e32 v108, 0xffff0000, v148
	v_fmac_f32_e32 v108, 0.5, v109
	v_lshlrev_b32_e32 v109, 16, v149
	v_fmac_f32_e32 v109, 0.5, v110
	v_and_b32_e32 v110, 0xffff0000, v149
	v_fmac_f32_e32 v110, 0.5, v111
	v_lshlrev_b32_e32 v111, 16, v150
	v_and_b32_e32 v115, 0xffff0000, v150
	v_fmac_f32_e32 v111, 0.5, v104
	v_fmac_f32_e32 v115, 0.5, v105
	v_cvt_pk_bf16_f32 v104, v114, v108
	v_cvt_pk_bf16_f32 v105, v109, v110
	v_mul_f32_e32 v108, v108, v108
	v_mul_f32_e32 v110, v110, v110
	v_and_b32_e32 v117, 0xffff0000, v151
	v_fmac_f32_e32 v108, v114, v114
	v_fmac_f32_e32 v110, v109, v109
	v_mul_f32_e32 v109, v115, v115
	v_lshlrev_b32_e32 v116, 16, v151
	v_fmac_f32_e32 v117, 0.5, v107
	v_add_f32_e32 v108, v108, v110
	v_fmac_f32_e32 v109, v111, v111
	v_fmac_f32_e32 v116, 0.5, v106
	v_add_f32_e32 v108, v109, v108
	v_mul_f32_e32 v109, v117, v117
	v_fmac_f32_e32 v109, v116, v116
	v_add_f32_e32 v108, v109, v108
	v_lshlrev_b32_e32 v109, 16, v144
	v_fmac_f32_e32 v109, 0.5, v100
	v_and_b32_e32 v100, 0xffff0000, v144
	v_and_b32_e32 v110, 0xffff0000, v145
	v_cvt_pk_bf16_f32 v106, v111, v115
	v_fmac_f32_e32 v100, 0.5, v101
	v_lshlrev_b32_e32 v101, 16, v145
	v_fmac_f32_e32 v110, 0.5, v103
	v_lshlrev_b32_e32 v111, 16, v146
	v_and_b32_e32 v114, 0xffff0000, v146
	v_fmac_f32_e32 v101, 0.5, v102
	v_fmac_f32_e32 v111, 0.5, v96
	v_fmac_f32_e32 v114, 0.5, v97
	v_mul_f32_e32 v96, v100, v100
	v_mul_f32_e32 v97, v110, v110
	v_fmac_f32_e32 v96, v109, v109
	v_fmac_f32_e32 v97, v101, v101
	v_cvt_pk_bf16_f32 v107, v116, v117
	v_and_b32_e32 v116, 0xffff0000, v147
	v_add_f32_e32 v96, v96, v97
	v_mul_f32_e32 v97, v114, v114
	v_lshlrev_b32_e32 v115, 16, v147
	v_fmac_f32_e32 v116, 0.5, v99
	v_fmac_f32_e32 v97, v111, v111
	v_fmac_f32_e32 v115, 0.5, v98
	v_add_f32_e32 v96, v97, v96
	v_mul_f32_e32 v97, v116, v116
	v_fmac_f32_e32 v97, v115, v115
	v_add_f32_e32 v96, v97, v96
	v_add_f32_e32 v99, v108, v96
	v_mov_b32_e32 v108, v99
	s_nop 1
	v_permlane16_swap_b32_e32 v108, v99
	s_waitcnt lgkmcnt(0)
	v_lshlrev_b64 v[112:113], 11, v[178:179]
	v_lshl_add_u64 v[96:97], v[112:113], 1, s[52:53]
	v_lshl_add_u64 v[102:103], v[168:169], 1, v[96:97]
	global_store_dwordx4 v[102:103], v[104:107], off
	s_waitcnt lgkmcnt(0)
	v_add_f32_e32 v96, v99, v108
	v_mov_b32_e32 v97, v96
	s_nop 1
	v_permlane32_swap_b32_e32 v97, v96
	v_cvt_pk_bf16_f32 v98, v109, v100
	v_cvt_pk_bf16_f32 v99, v101, v110
	v_cvt_pk_bf16_f32 v100, v111, v114
	v_cvt_pk_bf16_f32 v101, v115, v116
	global_store_dwordx4 v[102:103], v[98:101], off offset:256
	s_and_saveexec_b64 s[58:59], s[42:43]
	s_cbranch_execz .LBB0_293
; __device__ __forceinline__ unsigned cvt_pk_bf16(float lo, float hi) { unsigned r; asm volatile("v_cvt_pk_bf16_f32 %0, %1, %2" : "=v"(r) : "v"(lo), "v"(hi)); return r; }
; __device__ __forceinline__ float xlane_add(float v, int lane_, int mask) { return v + __uint_as_float((unsigned)__builtin_amdgcn_ds_bpermute((lane_ ^ mask) << 2, (int)__float_as_uint(v))); }
;     __device__ __forceinline__ void operator()(const f32x4 (&acc)[2][2][4][2], const Unit& u, int wr, int wc, int fr, int fq) const {
;     ...
;             for (int m = 0; m < 4; ++m) { float ss = 0.f; const int row = row0 + ai * HALF + m * 16;
; #pragma unroll
;                 for (int bj = 0; bj < 2; ++bj) { const u32x4 xw = xa[m][bj]; const f32x4 a0 = acc[ai][bj][m][0], a1 = acc[ai][bj][m][1];
;                     const float v0 = __uint_as_float(xw.x << 16) + a0[0] * alpha, v1 = __uint_as_float(xw.x & 0xffff0000u) + a0[1] * alpha, v2 = __uint_as_float(xw.y << 16) + a0[2] * alpha, v3 = __uint_as_float(xw.y & 0xffff0000u) + a0[3] * alpha;
;                     const float v4 = __uint_as_float(xw.z << 16) + a1[0] * alpha, v5 = __uint_as_float(xw.z & 0xffff0000u) + a1[1] * alpha, v6 = __uint_as_float(xw.w << 16) + a1[2] * alpha, v7 = __uint_as_float(xw.w & 0xffff0000u) + a1[3] * alpha;
;                     u32x4 w; w.x = cvt_pk_bf16(v0, v1); w.y = cvt_pk_bf16(v2, v3); w.z = cvt_pk_bf16(v4, v5); w.w = cvt_pk_bf16(v6, v7);
;                     *(__attribute__((address_space(1))) u32x4*)(D + (size_t)row * ldx + col0 + bj * HALF) = w;
;                     ss += (v0 * v0 + v1 * v1) + (v2 * v2 + v3 * v3) + (v4 * v4 + v5 * v5) + (v6 * v6 + v7 * v7); }
;                 ss = xlane_add(ss, lane_, 16); ss = xlane_add(ss, lane_, 32);
;                 if (fq == 0) ((__attribute__((address_space(1))) float*)ssq)[(size_t)slot * mrows + row] = ss; }
	s_add_u32 s38, s74, s61
	s_addc_u32 s39, s75, s60
	s_waitcnt lgkmcnt(0)
	v_add_f32_e32 v98, v96, v97
	v_lshl_add_u64 v[96:97], v[166:167], 2, s[38:39]
	global_store_dword v[96:97], v98, off offset:64
.LBB0_293:
	s_or_b64 exec, exec, s[58:59]
	v_lshlrev_b32_e32 v98, 16, v140
	v_fmac_f32_e32 v98, 0.5, v92
	v_and_b32_e32 v92, 0xffff0000, v140
	v_fmac_f32_e32 v92, 0.5, v93
	v_lshlrev_b32_e32 v93, 16, v141
	v_fmac_f32_e32 v93, 0.5, v94
	v_and_b32_e32 v94, 0xffff0000, v141
	v_fmac_f32_e32 v94, 0.5, v95
	v_lshlrev_b32_e32 v95, 16, v142
	v_and_b32_e32 v99, 0xffff0000, v142
	v_fmac_f32_e32 v95, 0.5, v88
	v_fmac_f32_e32 v99, 0.5, v89
	v_cvt_pk_bf16_f32 v88, v98, v92
	v_cvt_pk_bf16_f32 v89, v93, v94
	v_mul_f32_e32 v92, v92, v92
	v_mul_f32_e32 v94, v94, v94
	v_and_b32_e32 v101, 0xffff0000, v143
	v_fmac_f32_e32 v92, v98, v98
	v_fmac_f32_e32 v94, v93, v93
	v_mul_f32_e32 v93, v99, v99
	v_lshlrev_b32_e32 v100, 16, v143
	v_fmac_f32_e32 v101, 0.5, v91
	v_add_f32_e32 v92, v92, v94
	v_fmac_f32_e32 v93, v95, v95
	v_fmac_f32_e32 v100, 0.5, v90
	v_add_f32_e32 v92, v93, v92
	v_mul_f32_e32 v93, v101, v101
	v_fmac_f32_e32 v93, v100, v100
	v_add_f32_e32 v92, v93, v92
	v_lshlrev_b32_e32 v93, 16, v136
	v_fmac_f32_e32 v93, 0.5, v84
	v_and_b32_e32 v84, 0xffff0000, v136
	v_and_b32_e32 v94, 0xffff0000, v137
	v_cvt_pk_bf16_f32 v90, v95, v99
	v_fmac_f32_e32 v84, 0.5, v85
	v_lshlrev_b32_e32 v85, 16, v137
	v_fmac_f32_e32 v94, 0.5, v87
	v_lshlrev_b32_e32 v95, 16, v138
	v_and_b32_e32 v98, 0xffff0000, v138
	v_fmac_f32_e32 v85, 0.5, v86
	v_fmac_f32_e32 v95, 0.5, v80
	v_fmac_f32_e32 v98, 0.5, v81
	v_mul_f32_e32 v80, v84, v84
	v_mul_f32_e32 v81, v94, v94
	v_fmac_f32_e32 v80, v93, v93
	v_fmac_f32_e32 v81, v85, v85
	v_cvt_pk_bf16_f32 v91, v100, v101
	v_and_b32_e32 v100, 0xffff0000, v139
	v_add_f32_e32 v80, v80, v81
	v_mul_f32_e32 v81, v98, v98
	v_lshlrev_b32_e32 v99, 16, v139
	v_fmac_f32_e32 v100, 0.5, v83
	v_fmac_f32_e32 v81, v95, v95
	v_fmac_f32_e32 v99, 0.5, v82
	v_add_f32_e32 v80, v81, v80
	v_mul_f32_e32 v81, v100, v100
	v_fmac_f32_e32 v81, v99, v99
	v_add_f32_e32 v80, v81, v80
	v_add_f32_e32 v83, v92, v80
	v_mov_b32_e32 v92, v83
	s_nop 1
	v_permlane16_swap_b32_e32 v92, v83
	s_waitcnt lgkmcnt(0)
	v_lshlrev_b64 v[96:97], 11, v[176:177]
	v_lshl_add_u64 v[80:81], v[96:97], 1, s[52:53]
	v_lshl_add_u64 v[86:87], v[168:169], 1, v[80:81]
	global_store_dwordx4 v[86:87], v[88:91], off
	s_waitcnt lgkmcnt(0)
	v_add_f32_e32 v80, v83, v92
	v_mov_b32_e32 v81, v80
	s_nop 1
	v_permlane32_swap_b32_e32 v81, v80
	v_cvt_pk_bf16_f32 v82, v93, v84
	v_cvt_pk_bf16_f32 v83, v85, v94
	v_cvt_pk_bf16_f32 v84, v95, v98
	v_cvt_pk_bf16_f32 v85, v99, v100
	global_store_dwordx4 v[86:87], v[82:85], off offset:256
	s_and_saveexec_b64 s[58:59], s[42:43]
	s_cbranch_execz .LBB0_295
	s_add_u32 s38, s74, s61
	s_addc_u32 s39, s75, s60
	s_waitcnt lgkmcnt(0)
	v_add_f32_e32 v82, v80, v81
	v_lshl_add_u64 v[80:81], v[166:167], 2, s[38:39]
	global_store_dword v[80:81], v82, off offset:128
.LBB0_295:
	s_or_b64 exec, exec, s[58:59]
	v_lshlrev_b32_e32 v82, 16, v132
	v_fmac_f32_e32 v82, 0.5, v76
	v_and_b32_e32 v76, 0xffff0000, v132
	v_fmac_f32_e32 v76, 0.5, v77
	v_lshlrev_b32_e32 v77, 16, v133
	v_fmac_f32_e32 v77, 0.5, v78
	v_and_b32_e32 v78, 0xffff0000, v133
	v_fmac_f32_e32 v78, 0.5, v79
	v_lshlrev_b32_e32 v79, 16, v134
	v_and_b32_e32 v83, 0xffff0000, v134
	v_fmac_f32_e32 v79, 0.5, v72
	v_fmac_f32_e32 v83, 0.5, v73
	v_cvt_pk_bf16_f32 v72, v82, v76
	v_cvt_pk_bf16_f32 v73, v77, v78
	v_mul_f32_e32 v76, v76, v76
	v_mul_f32_e32 v78, v78, v78
	v_and_b32_e32 v85, 0xffff0000, v135
	v_fmac_f32_e32 v76, v82, v82
	v_fmac_f32_e32 v78, v77, v77
	v_mul_f32_e32 v77, v83, v83
	v_lshlrev_b32_e32 v84, 16, v135
	v_fmac_f32_e32 v85, 0.5, v75
	v_add_f32_e32 v76, v76, v78
	v_fmac_f32_e32 v77, v79, v79
	v_fmac_f32_e32 v84, 0.5, v74
	v_add_f32_e32 v76, v77, v76
	v_mul_f32_e32 v77, v85, v85
	v_fmac_f32_e32 v77, v84, v84
	v_add_f32_e32 v76, v77, v76
	v_lshlrev_b32_e32 v77, 16, v120
	v_fmac_f32_e32 v77, 0.5, v68
	v_and_b32_e32 v68, 0xffff0000, v120
	v_and_b32_e32 v78, 0xffff0000, v121
	v_cvt_pk_bf16_f32 v74, v79, v83
	v_fmac_f32_e32 v68, 0.5, v69
	v_lshlrev_b32_e32 v69, 16, v121
	v_fmac_f32_e32 v78, 0.5, v71
	v_lshlrev_b32_e32 v79, 16, v122
	v_and_b32_e32 v82, 0xffff0000, v122
	v_fmac_f32_e32 v69, 0.5, v70
	v_fmac_f32_e32 v79, 0.5, v64
	v_fmac_f32_e32 v82, 0.5, v65
	v_mul_f32_e32 v64, v68, v68
	v_mul_f32_e32 v65, v78, v78
	v_fmac_f32_e32 v64, v77, v77
	v_fmac_f32_e32 v65, v69, v69
	v_cvt_pk_bf16_f32 v75, v84, v85
	v_and_b32_e32 v84, 0xffff0000, v123
	v_add_f32_e32 v64, v64, v65
	v_mul_f32_e32 v65, v82, v82
	v_lshlrev_b32_e32 v83, 16, v123
	v_fmac_f32_e32 v84, 0.5, v67
	v_fmac_f32_e32 v65, v79, v79
	v_fmac_f32_e32 v83, 0.5, v66
	v_add_f32_e32 v64, v65, v64
	v_mul_f32_e32 v65, v84, v84
	v_fmac_f32_e32 v65, v83, v83
	v_add_f32_e32 v64, v65, v64
	v_add_f32_e32 v67, v76, v64
	v_mov_b32_e32 v76, v67
	s_nop 1
	v_permlane16_swap_b32_e32 v76, v67
	s_waitcnt lgkmcnt(0)
	v_lshlrev_b64 v[80:81], 11, v[174:175]
	v_lshl_add_u64 v[64:65], v[80:81], 1, s[52:53]
	v_lshl_add_u64 v[70:71], v[168:169], 1, v[64:65]
	global_store_dwordx4 v[70:71], v[72:75], off
	s_waitcnt lgkmcnt(0)
	v_add_f32_e32 v64, v67, v76
	v_mov_b32_e32 v65, v64
	s_nop 1
	v_permlane32_swap_b32_e32 v65, v64
	v_cvt_pk_bf16_f32 v66, v77, v68
	v_cvt_pk_bf16_f32 v67, v69, v78
	v_cvt_pk_bf16_f32 v68, v79, v82
	v_cvt_pk_bf16_f32 v69, v83, v84
	global_store_dwordx4 v[70:71], v[66:69], off offset:256
	s_and_saveexec_b64 s[58:59], s[42:43]
	s_cbranch_execz .LBB0_297
	s_add_u32 s38, s74, s61
	s_addc_u32 s39, s75, s60
	s_waitcnt lgkmcnt(0)
	v_add_f32_e32 v66, v64, v65
	v_lshl_add_u64 v[64:65], v[166:167], 2, s[38:39]
	global_store_dword v[64:65], v66, off offset:192
; __device__ __forceinline__ unsigned cvt_pk_bf16(float lo, float hi) { unsigned r; asm volatile("v_cvt_pk_bf16_f32 %0, %1, %2" : "=v"(r) : "v"(lo), "v"(hi)); return r; }
; __device__ __forceinline__ float xlane_add(float v, int lane_, int mask) { return v + __uint_as_float((unsigned)__builtin_amdgcn_ds_bpermute((lane_ ^ mask) << 2, (int)__float_as_uint(v))); }
;     __device__ __forceinline__ void operator()(const f32x4 (&acc)[2][2][4][2], const Unit& u, int wr, int wc, int fr, int fq) const {
;     ...
;         for (int ai = 0; ai < 2; ++ai) { u32x4 xa[4][2];
; #pragma unroll
;             for (int m = 0; m < 4; ++m)
; #pragma unroll
;                 for (int bj = 0; bj < 2; ++bj) xa[m][bj] = *(const __attribute__((address_space(1))) u32x4*)(S + (size_t)(row0 + ai * HALF + m * 16) * ldx + col0 + bj * HALF);
; #pragma unroll
;             for (int m = 0; m < 4; ++m) { float ss = 0.f; const int row = row0 + ai * HALF + m * 16;
; #pragma unroll
;                 for (int bj = 0; bj < 2; ++bj) { const u32x4 xw = xa[m][bj]; const f32x4 a0 = acc[ai][bj][m][0], a1 = acc[ai][bj][m][1];
;                     const float v0 = __uint_as_float(xw.x << 16) + a0[0] * alpha, v1 = __uint_as_float(xw.x & 0xffff0000u) + a0[1] * alpha, v2 = __uint_as_float(xw.y << 16) + a0[2] * alpha, v3 = __uint_as_float(xw.y & 0xffff0000u) + a0[3] * alpha;
;                     const float v4 = __uint_as_float(xw.z << 16) + a1[0] * alpha, v5 = __uint_as_float(xw.z & 0xffff0000u) + a1[1] * alpha, v6 = __uint_as_float(xw.w << 16) + a1[2] * alpha, v7 = __uint_as_float(xw.w & 0xffff0000u) + a1[3] * alpha;
;                     u32x4 w; w.x = cvt_pk_bf16(v0, v1); w.y = cvt_pk_bf16(v2, v3); w.z = cvt_pk_bf16(v4, v5); w.w = cvt_pk_bf16(v6, v7);
;                     *(__attribute__((address_space(1))) u32x4*)(D + (size_t)row * ldx + col0 + bj * HALF) = w;
;                     ss += (v0 * v0 + v1 * v1) + (v2 * v2 + v3 * v3) + (v4 * v4 + v5 * v5) + (v6 * v6 + v7 * v7); }
;                 ss = xlane_add(ss, lane_, 16); ss = xlane_add(ss, lane_, 32);
;                 if (fq == 0) ((__attribute__((address_space(1))) float*)ssq)[(size_t)slot * mrows + row] = ss; }
.LBB0_297:
	s_or_b64 exec, exec, s[58:59]
	s_mov_b64 s[38:39], 0x80000
	v_lshl_add_u64 v[102:103], v[172:173], 0, s[38:39]
	s_waitcnt lgkmcnt(0)
	v_lshl_add_u64 v[64:65], v[170:171], 0, v[102:103]
	global_load_dwordx4 v[98:101], v[64:65], off
	global_load_dwordx4 v[88:91], v[64:65], off offset:256
	v_add_u32_e32 v96, 0x90, v166
	v_ashrrev_i32_e32 v97, 31, v96
	v_lshlrev_b64 v[64:65], 12, v[96:97]
	v_add_u32_e32 v94, 0xa0, v166
	v_lshl_add_u64 v[64:65], v[170:171], 0, v[64:65]
	v_ashrrev_i32_e32 v95, 31, v94
	global_load_dwordx4 v[84:87], v[64:65], off
	global_load_dwordx4 v[80:83], v[64:65], off offset:256
	v_lshlrev_b64 v[64:65], 12, v[94:95]
	v_add_u32_e32 v92, 0xb0, v166
	v_lshl_add_u64 v[64:65], v[170:171], 0, v[64:65]
	v_ashrrev_i32_e32 v93, 31, v92
	global_load_dwordx4 v[76:79], v[64:65], off
	global_load_dwordx4 v[72:75], v[64:65], off offset:256
	v_lshlrev_b64 v[64:65], 12, v[92:93]
	v_lshl_add_u64 v[64:65], v[170:171], 0, v[64:65]
	global_load_dwordx4 v[68:71], v[64:65], off
	s_nop 0
	global_load_dwordx4 v[64:67], v[64:65], off offset:256
	s_waitcnt vmcnt(7)
	v_lshlrev_b32_e32 v105, 16, v99
	v_lshlrev_b32_e32 v104, 16, v98
	v_and_b32_e32 v98, 0xffff0000, v98
	v_fmac_f32_e32 v105, 0.5, v62
	v_and_b32_e32 v62, 0xffff0000, v99
	v_fmac_f32_e32 v104, 0.5, v60
	v_fmac_f32_e32 v98, 0.5, v61
	v_fmac_f32_e32 v62, 0.5, v63
	v_lshlrev_b32_e32 v63, 16, v100
	v_and_b32_e32 v99, 0xffff0000, v100
	v_lshl_add_u64 v[60:61], s[52:53], 0, v[102:103]
	v_fmac_f32_e32 v63, 0.5, v56
	v_fmac_f32_e32 v99, 0.5, v57
	v_lshlrev_b32_e32 v100, 16, v101
	v_and_b32_e32 v101, 0xffff0000, v101
	v_cvt_pk_bf16_f32 v56, v104, v98
	v_cvt_pk_bf16_f32 v57, v105, v62
	v_lshl_add_u64 v[60:61], v[168:169], 1, v[60:61]
	v_fmac_f32_e32 v100, 0.5, v58
	v_fmac_f32_e32 v101, 0.5, v59
	v_cvt_pk_bf16_f32 v58, v63, v99
	v_cvt_pk_bf16_f32 v59, v100, v101
	global_store_dwordx4 v[60:61], v[56:59], off
	s_nop 1
	v_mul_f32_e32 v56, v98, v98
	v_mul_f32_e32 v57, v62, v62
	v_fmac_f32_e32 v56, v104, v104
	v_fmac_f32_e32 v57, v105, v105
	v_add_f32_e32 v56, v56, v57
	v_mul_f32_e32 v57, v99, v99
	v_fmac_f32_e32 v57, v63, v63
	v_add_f32_e32 v56, v57, v56
	v_mul_f32_e32 v57, v101, v101
	v_fmac_f32_e32 v57, v100, v100
	v_add_f32_e32 v56, v57, v56
	s_waitcnt vmcnt(7)
	v_lshlrev_b32_e32 v57, 16, v88
	v_fmac_f32_e32 v57, 0.5, v52
	v_and_b32_e32 v52, 0xffff0000, v88
	v_fmac_f32_e32 v52, 0.5, v53
	v_lshlrev_b32_e32 v53, 16, v89
	v_fmac_f32_e32 v53, 0.5, v54
	v_and_b32_e32 v54, 0xffff0000, v89
	v_fmac_f32_e32 v54, 0.5, v55
	v_lshlrev_b32_e32 v55, 16, v90
	v_and_b32_e32 v58, 0xffff0000, v90
	v_fmac_f32_e32 v55, 0.5, v48
	v_fmac_f32_e32 v58, 0.5, v49
	v_lshlrev_b32_e32 v59, 16, v91
	v_and_b32_e32 v62, 0xffff0000, v91
	v_cvt_pk_bf16_f32 v48, v57, v52
	v_cvt_pk_bf16_f32 v49, v53, v54
	v_fmac_f32_e32 v59, 0.5, v50
	v_fmac_f32_e32 v62, 0.5, v51
	v_cvt_pk_bf16_f32 v50, v55, v58
	v_cvt_pk_bf16_f32 v51, v59, v62
	global_store_dwordx4 v[60:61], v[48:51], off offset:256
	s_nop 1
	v_mul_f32_e32 v48, v52, v52
	v_mul_f32_e32 v49, v54, v54
	v_fmac_f32_e32 v48, v57, v57
	v_fmac_f32_e32 v49, v53, v53
	v_add_f32_e32 v48, v48, v49
	v_mul_f32_e32 v49, v58, v58
	v_fmac_f32_e32 v49, v55, v55
	v_add_f32_e32 v48, v49, v48
	v_mul_f32_e32 v49, v62, v62
	v_fmac_f32_e32 v49, v59, v59
	v_add_f32_e32 v48, v49, v48
	v_add_f32_e32 v48, v56, v48
	v_mov_b32_e32 v49, v48
	s_nop 1
	v_permlane16_swap_b32_e32 v49, v48
	s_waitcnt lgkmcnt(0)
	v_add_f32_e32 v48, v48, v49
	v_mov_b32_e32 v49, v48
	s_nop 1
	v_permlane32_swap_b32_e32 v49, v48
	s_and_saveexec_b64 s[58:59], s[42:43]
	s_cbranch_execz .LBB0_299
	s_add_u32 s38, s74, s61
	s_addc_u32 s39, s75, s60
	s_waitcnt lgkmcnt(0)
	v_add_f32_e32 v50, v48, v49
	v_lshl_add_u64 v[48:49], v[166:167], 2, s[38:39]
	global_store_dword v[48:49], v50, off offset:512
.LBB0_299:
	s_or_b64 exec, exec, s[58:59]
	s_waitcnt vmcnt(7)
	v_lshlrev_b32_e32 v50, 16, v84
	v_fmac_f32_e32 v50, 0.5, v44
	v_and_b32_e32 v44, 0xffff0000, v84
	v_fmac_f32_e32 v44, 0.5, v45
	v_lshlrev_b32_e32 v45, 16, v85
	v_fmac_f32_e32 v45, 0.5, v46
	v_and_b32_e32 v46, 0xffff0000, v85
	v_fmac_f32_e32 v46, 0.5, v47
	v_lshlrev_b32_e32 v47, 16, v86
	v_and_b32_e32 v51, 0xffff0000, v86
	v_fmac_f32_e32 v47, 0.5, v40
	v_fmac_f32_e32 v51, 0.5, v41
	v_cvt_pk_bf16_f32 v40, v50, v44
	v_cvt_pk_bf16_f32 v41, v45, v46
	v_mul_f32_e32 v44, v44, v44
	v_mul_f32_e32 v46, v46, v46
	v_and_b32_e32 v53, 0xffff0000, v87
	v_fmac_f32_e32 v44, v50, v50
	v_fmac_f32_e32 v46, v45, v45
	v_mul_f32_e32 v45, v51, v51
	v_lshlrev_b32_e32 v52, 16, v87
	v_fmac_f32_e32 v53, 0.5, v43
	v_add_f32_e32 v44, v44, v46
	v_fmac_f32_e32 v45, v47, v47
	v_fmac_f32_e32 v52, 0.5, v42
	v_add_f32_e32 v44, v45, v44
	v_mul_f32_e32 v45, v53, v53
	v_fmac_f32_e32 v45, v52, v52
	v_add_f32_e32 v44, v45, v44
	s_waitcnt vmcnt(6)
	v_lshlrev_b32_e32 v45, 16, v80
	v_fmac_f32_e32 v45, 0.5, v36
	v_and_b32_e32 v36, 0xffff0000, v80
	v_and_b32_e32 v46, 0xffff0000, v81
	v_cvt_pk_bf16_f32 v42, v47, v51
	v_fmac_f32_e32 v36, 0.5, v37
	v_lshlrev_b32_e32 v37, 16, v81
	v_fmac_f32_e32 v46, 0.5, v39
	v_lshlrev_b32_e32 v47, 16, v82
	v_and_b32_e32 v50, 0xffff0000, v82
	v_fmac_f32_e32 v37, 0.5, v38
	v_fmac_f32_e32 v47, 0.5, v32
	v_fmac_f32_e32 v50, 0.5, v33
	v_mul_f32_e32 v32, v36, v36
	v_mul_f32_e32 v33, v46, v46
	v_fmac_f32_e32 v32, v45, v45
	v_fmac_f32_e32 v33, v37, v37
	v_cvt_pk_bf16_f32 v43, v52, v53
	v_and_b32_e32 v52, 0xffff0000, v83
	v_add_f32_e32 v32, v32, v33
	v_mul_f32_e32 v33, v50, v50
	v_lshlrev_b32_e32 v51, 16, v83
	v_fmac_f32_e32 v52, 0.5, v35
	v_fmac_f32_e32 v33, v47, v47
	v_fmac_f32_e32 v51, 0.5, v34
	v_add_f32_e32 v32, v33, v32
	v_mul_f32_e32 v33, v52, v52
	v_fmac_f32_e32 v33, v51, v51
	v_add_f32_e32 v32, v33, v32
	v_add_f32_e32 v35, v44, v32
	v_mov_b32_e32 v44, v35
	s_nop 1
	v_permlane16_swap_b32_e32 v44, v35
	s_waitcnt lgkmcnt(0)
	v_lshlrev_b64 v[48:49], 11, v[96:97]
	v_lshl_add_u64 v[32:33], v[48:49], 1, s[52:53]
	v_lshl_add_u64 v[38:39], v[168:169], 1, v[32:33]
	global_store_dwordx4 v[38:39], v[40:43], off
	s_waitcnt lgkmcnt(0)
	v_add_f32_e32 v32, v35, v44
	v_mov_b32_e32 v33, v32
	s_nop 1
	v_permlane32_swap_b32_e32 v33, v32
	v_cvt_pk_bf16_f32 v34, v45, v36
	v_cvt_pk_bf16_f32 v35, v37, v46
	v_cvt_pk_bf16_f32 v36, v47, v50
	v_cvt_pk_bf16_f32 v37, v51, v52
	global_store_dwordx4 v[38:39], v[34:37], off offset:256
	s_and_saveexec_b64 s[58:59], s[42:43]
	s_cbranch_execz .LBB0_301
	s_add_u32 s38, s74, s61
	s_addc_u32 s39, s75, s60
	s_waitcnt lgkmcnt(0)
	v_add_f32_e32 v34, v32, v33
	v_lshl_add_u64 v[32:33], v[166:167], 2, s[38:39]
	global_store_dword v[32:33], v34, off offset:576
; __device__ __forceinline__ unsigned cvt_pk_bf16(float lo, float hi) { unsigned r; asm volatile("v_cvt_pk_bf16_f32 %0, %1, %2" : "=v"(r) : "v"(lo), "v"(hi)); return r; }
; __device__ __forceinline__ float xlane_add(float v, int lane_, int mask) { return v + __uint_as_float((unsigned)__builtin_amdgcn_ds_bpermute((lane_ ^ mask) << 2, (int)__float_as_uint(v))); }
;     __device__ __forceinline__ void operator()(const f32x4 (&acc)[2][2][4][2], const Unit& u, int wr, int wc, int fr, int fq) const {
;     ...
;             for (int m = 0; m < 4; ++m) { float ss = 0.f; const int row = row0 + ai * HALF + m * 16;
; #pragma unroll
;                 for (int bj = 0; bj < 2; ++bj) { const u32x4 xw = xa[m][bj]; const f32x4 a0 = acc[ai][bj][m][0], a1 = acc[ai][bj][m][1];
;                     const float v0 = __uint_as_float(xw.x << 16) + a0[0] * alpha, v1 = __uint_as_float(xw.x & 0xffff0000u) + a0[1] * alpha, v2 = __uint_as_float(xw.y << 16) + a0[2] * alpha, v3 = __uint_as_float(xw.y & 0xffff0000u) + a0[3] * alpha;
;                     const float v4 = __uint_as_float(xw.z << 16) + a1[0] * alpha, v5 = __uint_as_float(xw.z & 0xffff0000u) + a1[1] * alpha, v6 = __uint_as_float(xw.w << 16) + a1[2] * alpha, v7 = __uint_as_float(xw.w & 0xffff0000u) + a1[3] * alpha;
;                     u32x4 w; w.x = cvt_pk_bf16(v0, v1); w.y = cvt_pk_bf16(v2, v3); w.z = cvt_pk_bf16(v4, v5); w.w = cvt_pk_bf16(v6, v7);
;                     *(__attribute__((address_space(1))) u32x4*)(D + (size_t)row * ldx + col0 + bj * HALF) = w;
;                     ss += (v0 * v0 + v1 * v1) + (v2 * v2 + v3 * v3) + (v4 * v4 + v5 * v5) + (v6 * v6 + v7 * v7); }
;                 ss = xlane_add(ss, lane_, 16); ss = xlane_add(ss, lane_, 32);
;                 if (fq == 0) ((__attribute__((address_space(1))) float*)ssq)[(size_t)slot * mrows + row] = ss; }
.LBB0_301:
	s_or_b64 exec, exec, s[58:59]
	s_waitcnt vmcnt(7)
	v_lshlrev_b32_e32 v34, 16, v76
	v_fmac_f32_e32 v34, 0.5, v28
	v_and_b32_e32 v28, 0xffff0000, v76
	v_fmac_f32_e32 v28, 0.5, v29
	v_lshlrev_b32_e32 v29, 16, v77
	v_fmac_f32_e32 v29, 0.5, v30
	v_and_b32_e32 v30, 0xffff0000, v77
	v_fmac_f32_e32 v30, 0.5, v31
	v_lshlrev_b32_e32 v31, 16, v78
	v_and_b32_e32 v35, 0xffff0000, v78
	v_fmac_f32_e32 v31, 0.5, v24
	v_fmac_f32_e32 v35, 0.5, v25
	v_cvt_pk_bf16_f32 v24, v34, v28
	v_cvt_pk_bf16_f32 v25, v29, v30
	v_mul_f32_e32 v28, v28, v28
	v_mul_f32_e32 v30, v30, v30
	v_and_b32_e32 v37, 0xffff0000, v79
	v_fmac_f32_e32 v28, v34, v34
	v_fmac_f32_e32 v30, v29, v29
	v_mul_f32_e32 v29, v35, v35
	v_lshlrev_b32_e32 v36, 16, v79
	v_fmac_f32_e32 v37, 0.5, v27
	v_add_f32_e32 v28, v28, v30
	v_fmac_f32_e32 v29, v31, v31
	v_fmac_f32_e32 v36, 0.5, v26
	v_add_f32_e32 v28, v29, v28
	v_mul_f32_e32 v29, v37, v37
	v_fmac_f32_e32 v29, v36, v36
	v_add_f32_e32 v28, v29, v28
	s_waitcnt vmcnt(6)
	v_lshlrev_b32_e32 v29, 16, v72
	v_fmac_f32_e32 v29, 0.5, v20
	v_and_b32_e32 v20, 0xffff0000, v72
	v_and_b32_e32 v30, 0xffff0000, v73
	v_cvt_pk_bf16_f32 v26, v31, v35
	v_fmac_f32_e32 v20, 0.5, v21
	v_lshlrev_b32_e32 v21, 16, v73
	v_fmac_f32_e32 v30, 0.5, v23
	v_lshlrev_b32_e32 v31, 16, v74
	v_and_b32_e32 v34, 0xffff0000, v74
	v_fmac_f32_e32 v21, 0.5, v22
	v_fmac_f32_e32 v31, 0.5, v16
	v_fmac_f32_e32 v34, 0.5, v17
	v_mul_f32_e32 v16, v20, v20
	v_mul_f32_e32 v17, v30, v30
	v_fmac_f32_e32 v16, v29, v29
	v_fmac_f32_e32 v17, v21, v21
	v_cvt_pk_bf16_f32 v27, v36, v37
	v_and_b32_e32 v36, 0xffff0000, v75
	v_add_f32_e32 v16, v16, v17
	v_mul_f32_e32 v17, v34, v34
	v_lshlrev_b32_e32 v35, 16, v75
	v_fmac_f32_e32 v36, 0.5, v19
	v_fmac_f32_e32 v17, v31, v31
	v_fmac_f32_e32 v35, 0.5, v18
	v_add_f32_e32 v16, v17, v16
	v_mul_f32_e32 v17, v36, v36
	v_fmac_f32_e32 v17, v35, v35
	v_add_f32_e32 v16, v17, v16
	v_add_f32_e32 v19, v28, v16
	v_mov_b32_e32 v28, v19
	s_nop 1
	v_permlane16_swap_b32_e32 v28, v19
	s_waitcnt lgkmcnt(0)
	v_lshlrev_b64 v[32:33], 11, v[94:95]
	v_lshl_add_u64 v[16:17], v[32:33], 1, s[52:53]
	v_lshl_add_u64 v[22:23], v[168:169], 1, v[16:17]
	global_store_dwordx4 v[22:23], v[24:27], off
	s_waitcnt lgkmcnt(0)
	v_add_f32_e32 v16, v19, v28
	v_mov_b32_e32 v17, v16
	s_nop 1
	v_permlane32_swap_b32_e32 v17, v16
	v_cvt_pk_bf16_f32 v18, v29, v20
	v_cvt_pk_bf16_f32 v19, v21, v30
	v_cvt_pk_bf16_f32 v20, v31, v34
	v_cvt_pk_bf16_f32 v21, v35, v36
	global_store_dwordx4 v[22:23], v[18:21], off offset:256
	s_and_saveexec_b64 s[58:59], s[42:43]
	s_cbranch_execz .LBB0_303
	s_add_u32 s38, s74, s61
	s_addc_u32 s39, s75, s60
	s_waitcnt lgkmcnt(0)
	v_add_f32_e32 v18, v16, v17
	v_lshl_add_u64 v[16:17], v[166:167], 2, s[38:39]
	global_store_dword v[16:17], v18, off offset:640
.LBB0_303:
	s_or_b64 exec, exec, s[58:59]
	s_waitcnt vmcnt(7)
	v_lshlrev_b32_e32 v18, 16, v68
	v_fmac_f32_e32 v18, 0.5, v12
	v_and_b32_e32 v12, 0xffff0000, v68
	v_fmac_f32_e32 v12, 0.5, v13
	v_lshlrev_b32_e32 v13, 16, v69
	v_fmac_f32_e32 v13, 0.5, v14
	v_and_b32_e32 v14, 0xffff0000, v69
	v_fmac_f32_e32 v14, 0.5, v15
	v_lshlrev_b32_e32 v15, 16, v70
	v_and_b32_e32 v19, 0xffff0000, v70
	v_fmac_f32_e32 v15, 0.5, v8
	v_fmac_f32_e32 v19, 0.5, v9
	v_cvt_pk_bf16_f32 v8, v18, v12
	v_cvt_pk_bf16_f32 v9, v13, v14
	v_mul_f32_e32 v12, v12, v12
	v_mul_f32_e32 v14, v14, v14
	v_and_b32_e32 v21, 0xffff0000, v71
	v_fmac_f32_e32 v12, v18, v18
	v_fmac_f32_e32 v14, v13, v13
	v_mul_f32_e32 v13, v19, v19
	v_lshlrev_b32_e32 v20, 16, v71
	v_fmac_f32_e32 v21, 0.5, v11
	v_add_f32_e32 v12, v12, v14
	v_fmac_f32_e32 v13, v15, v15
	v_fmac_f32_e32 v20, 0.5, v10
	v_add_f32_e32 v12, v13, v12
	v_mul_f32_e32 v13, v21, v21
	v_fmac_f32_e32 v13, v20, v20
	v_add_f32_e32 v12, v13, v12
	s_waitcnt vmcnt(6)
	v_lshlrev_b32_e32 v13, 16, v64
	v_fmac_f32_e32 v13, 0.5, v4
	v_and_b32_e32 v4, 0xffff0000, v64
	v_and_b32_e32 v14, 0xffff0000, v65
	v_cvt_pk_bf16_f32 v10, v15, v19
	v_fmac_f32_e32 v4, 0.5, v5
	v_lshlrev_b32_e32 v5, 16, v65
	v_fmac_f32_e32 v14, 0.5, v7
	v_lshlrev_b32_e32 v15, 16, v66
	v_and_b32_e32 v18, 0xffff0000, v66
	v_fmac_f32_e32 v5, 0.5, v6
	v_fmac_f32_e32 v15, 0.5, v0
	v_fmac_f32_e32 v18, 0.5, v1
	v_mul_f32_e32 v0, v4, v4
	v_mul_f32_e32 v1, v14, v14
	v_fmac_f32_e32 v0, v13, v13
	v_fmac_f32_e32 v1, v5, v5
	v_cvt_pk_bf16_f32 v11, v20, v21
	v_and_b32_e32 v20, 0xffff0000, v67
	v_add_f32_e32 v0, v0, v1
	v_mul_f32_e32 v1, v18, v18
	v_lshlrev_b32_e32 v19, 16, v67
	v_fmac_f32_e32 v20, 0.5, v3
	v_fmac_f32_e32 v1, v15, v15
	v_fmac_f32_e32 v19, 0.5, v2
	v_add_f32_e32 v0, v1, v0
	v_mul_f32_e32 v1, v20, v20
	v_fmac_f32_e32 v1, v19, v19
	v_add_f32_e32 v0, v1, v0
	v_add_f32_e32 v3, v12, v0
	v_mov_b32_e32 v12, v3
	s_nop 1
	v_permlane16_swap_b32_e32 v12, v3
	s_waitcnt lgkmcnt(0)
	v_lshlrev_b64 v[16:17], 11, v[92:93]
	v_lshl_add_u64 v[0:1], v[16:17], 1, s[52:53]
	v_lshl_add_u64 v[6:7], v[168:169], 1, v[0:1]
	global_store_dwordx4 v[6:7], v[8:11], off
	s_waitcnt lgkmcnt(0)
	v_add_f32_e32 v0, v3, v12
	v_mov_b32_e32 v1, v0
	s_nop 1
	v_permlane32_swap_b32_e32 v1, v0
	v_cvt_pk_bf16_f32 v2, v13, v4
	v_cvt_pk_bf16_f32 v3, v5, v14
	v_cvt_pk_bf16_f32 v4, v15, v18
	v_cvt_pk_bf16_f32 v5, v19, v20
	global_store_dwordx4 v[6:7], v[2:5], off offset:256
	s_and_saveexec_b64 s[58:59], s[42:43]
	s_cbranch_execz .LBB0_305
	s_add_u32 s38, s74, s61
	s_addc_u32 s39, s75, s60
	s_waitcnt lgkmcnt(0)
	v_add_f32_e32 v2, v0, v1
	v_lshl_add_u64 v[0:1], v[166:167], 2, s[38:39]
	global_store_dword v[0:1], v2, off offset:704

; __device__ __forceinline__ void grid_barrier_impl(int wave, unsigned G, unsigned xcc, volatile LAS unsigned* st) {
;     ...
;             st[0] = nloc; st[1] = nx;
.LBB0_317:
	v_readlane_b32 s38, v255, 8
	s_nop 1
	v_mov_b32_e32 v2, s38
	v_readlane_b32 s38, v255, 9
	ds_write_b32 v2, v1
	s_nop 0
	v_mov_b32_e32 v2, s38
	s_waitcnt lgkmcnt(0)
	ds_write_b32 v2, v0

; __device__ __forceinline__ unsigned cvt_pk_bf16(float lo, float hi) { unsigned r; asm volatile("v_cvt_pk_bf16_f32 %0, %1, %2" : "=v"(r) : "v"(lo), "v"(hi)); return r; }
; __device__ __forceinline__ float xlane_add(float v, int lane_, int mask) { return v + __uint_as_float((unsigned)__builtin_amdgcn_ds_bpermute((lane_ ^ mask) << 2, (int)__float_as_uint(v))); }
;     __device__ __forceinline__ void operator()(const f32x4 (&acc)[2][2][4][2], const Unit& u, int wr, int wc, int fr, int fq) const {
;     ...
;         for (int ai = 0; ai < 2; ++ai) { u32x4 xa[4][2];
; #pragma unroll
;             for (int m = 0; m < 4; ++m)
; #pragma unroll
;                 for (int bj = 0; bj < 2; ++bj) xa[m][bj] = *(const __attribute__((address_space(1))) u32x4*)(S + (size_t)(row0 + ai * HALF + m * 16) * ldx + col0 + bj * HALF);
; #pragma unroll
;             for (int m = 0; m < 4; ++m) { float ss = 0.f; const int row = row0 + ai * HALF + m * 16;
; #pragma unroll
;                 for (int bj = 0; bj < 2; ++bj) { const u32x4 xw = xa[m][bj]; const f32x4 a0 = acc[ai][bj][m][0], a1 = acc[ai][bj][m][1];
;                     const float v0 = __uint_as_float(xw.x << 16) + a0[0] * alpha, v1 = __uint_as_float(xw.x & 0xffff0000u) + a0[1] * alpha, v2 = __uint_as_float(xw.y << 16) + a0[2] * alpha, v3 = __uint_as_float(xw.y & 0xffff0000u) + a0[3] * alpha;
;                     const float v4 = __uint_as_float(xw.z << 16) + a1[0] * alpha, v5 = __uint_as_float(xw.z & 0xffff0000u) + a1[1] * alpha, v6 = __uint_as_float(xw.w << 16) + a1[2] * alpha, v7 = __uint_as_float(xw.w & 0xffff0000u) + a1[3] * alpha;
;                     u32x4 w; w.x = cvt_pk_bf16(v0, v1); w.y = cvt_pk_bf16(v2, v3); w.z = cvt_pk_bf16(v4, v5); w.w = cvt_pk_bf16(v6, v7);
;                     *(__attribute__((address_space(1))) u32x4*)(D + (size_t)row * ldx + col0 + bj * HALF) = w;
;                     ss += (v0 * v0 + v1 * v1) + (v2 * v2 + v3 * v3) + (v4 * v4 + v5 * v5) + (v6 * v6 + v7 * v7); }
;                 ss = xlane_add(ss, lane_, 16); ss = xlane_add(ss, lane_, 32);
;                 if (fq == 0) ((__attribute__((address_space(1))) float*)ssq)[(size_t)slot * mrows + row] = ss; }
.LBB0_1409:
	v_lshl_or_b32 v168, s84, 8, v182
	v_lshl_add_u32 v166, s85, 8, v180
	v_ashrrev_i32_e32 v169, 31, v168
	v_lshlrev_b64 v[190:191], 1, v[168:169]
	v_ashrrev_i32_e32 v167, 31, v166
	v_lshl_add_u64 v[170:171], s[50:51], 0, v[190:191]
	v_lshlrev_b64 v[172:173], 12, v[166:167]
	v_lshl_add_u64 v[128:129], v[170:171], 0, v[172:173]
	global_load_dwordx4 v[186:189], v[128:129], off
	global_load_dwordx4 v[152:155], v[128:129], off offset:256
	v_or_b32_e32 v178, 16, v166
	v_ashrrev_i32_e32 v179, 31, v178
	v_lshlrev_b64 v[128:129], 12, v[178:179]
	v_or_b32_e32 v176, 32, v166
	v_lshl_add_u64 v[128:129], v[170:171], 0, v[128:129]
	v_ashrrev_i32_e32 v177, 31, v176
	global_load_dwordx4 v[148:151], v[128:129], off
	global_load_dwordx4 v[144:147], v[128:129], off offset:256
	v_lshlrev_b64 v[128:129], 12, v[176:177]
	v_or_b32_e32 v174, 48, v166
	v_lshl_add_u64 v[128:129], v[170:171], 0, v[128:129]
	v_ashrrev_i32_e32 v175, 31, v174
	global_load_dwordx4 v[140:143], v[128:129], off
	global_load_dwordx4 v[132:135], v[128:129], off offset:256
	v_lshlrev_b64 v[128:129], 12, v[174:175]
	v_lshl_add_u64 v[128:129], v[170:171], 0, v[128:129]
	global_load_dwordx4 v[136:139], v[128:129], off
	s_nop 0
	global_load_dwordx4 v[128:131], v[128:129], off offset:256
	s_lshl_b32 s38, s84, 2
	s_or_b32 s55, s38, s77
	s_mul_hi_i32 s53, s55, 0x28000
	s_mul_i32 s55, s55, 0x28000
	s_waitcnt vmcnt(0)
	v_lshlrev_b32_e32 v192, 16, v186
	v_add_f32_e32 v192, v124, v192
	v_and_b32_e32 v124, 0xffff0000, v186
	v_add_f32_e32 v186, v125, v124
	v_lshlrev_b32_e32 v124, 16, v187
	v_add_f32_e32 v126, v126, v124
	v_and_b32_e32 v124, 0xffff0000, v187
	v_add_f32_e32 v127, v127, v124
	v_lshlrev_b32_e32 v124, 16, v188
	v_add_f32_e32 v187, v120, v124
	v_and_b32_e32 v120, 0xffff0000, v188
	v_add_f32_e32 v188, v121, v120
	v_lshlrev_b32_e32 v120, 16, v189
	v_add_f32_e32 v193, v122, v120
	v_and_b32_e32 v120, 0xffff0000, v189
	v_lshl_add_u64 v[124:125], s[50:51], 0, v[172:173]
	v_add_f32_e32 v189, v123, v120
	v_cvt_pk_bf16_f32 v120, v192, v186
	v_cvt_pk_bf16_f32 v121, v126, v127
	v_lshl_add_u64 v[124:125], v[124:125], 0, v[190:191]
	v_cvt_pk_bf16_f32 v122, v187, v188
	v_cvt_pk_bf16_f32 v123, v193, v189
	global_store_dwordx4 v[124:125], v[120:123], off
	s_nop 1
	v_mul_f32_e32 v120, v186, v186
	v_mul_f32_e32 v121, v127, v127
	v_fmac_f32_e32 v120, v192, v192
	v_fmac_f32_e32 v121, v126, v126
	v_add_f32_e32 v120, v120, v121
	v_mul_f32_e32 v121, v188, v188
	v_fmac_f32_e32 v121, v187, v187
	v_add_f32_e32 v120, v121, v120
	v_mul_f32_e32 v121, v189, v189
	v_fmac_f32_e32 v121, v193, v193
	v_add_f32_e32 v120, v121, v120
	v_lshlrev_b32_e32 v121, 16, v152
	v_add_f32_e32 v116, v116, v121
	v_and_b32_e32 v121, 0xffff0000, v152
	v_add_f32_e32 v117, v117, v121
	v_lshlrev_b32_e32 v121, 16, v153
	v_add_f32_e32 v118, v118, v121
	v_and_b32_e32 v121, 0xffff0000, v153
	v_add_f32_e32 v119, v119, v121
	v_lshlrev_b32_e32 v121, 16, v154
	v_add_f32_e32 v121, v112, v121
	v_and_b32_e32 v112, 0xffff0000, v154
	v_add_f32_e32 v122, v113, v112
	v_lshlrev_b32_e32 v112, 16, v155
	v_add_f32_e32 v123, v114, v112
	v_and_b32_e32 v112, 0xffff0000, v155
	v_add_f32_e32 v126, v115, v112
	v_cvt_pk_bf16_f32 v112, v116, v117
	v_cvt_pk_bf16_f32 v113, v118, v119
	v_cvt_pk_bf16_f32 v114, v121, v122
	v_cvt_pk_bf16_f32 v115, v123, v126
	global_store_dwordx4 v[124:125], v[112:115], off offset:256
	s_nop 1
	v_mul_f32_e32 v112, v117, v117
	v_mul_f32_e32 v113, v119, v119
	v_fmac_f32_e32 v112, v116, v116
	v_fmac_f32_e32 v113, v118, v118
	v_add_f32_e32 v112, v112, v113
	v_mul_f32_e32 v113, v122, v122
	v_fmac_f32_e32 v113, v121, v121
	v_add_f32_e32 v112, v113, v112
	v_mul_f32_e32 v113, v126, v126
	v_fmac_f32_e32 v113, v123, v123
	v_add_f32_e32 v112, v113, v112
	v_add_f32_e32 v112, v120, v112
	v_mov_b32_e32 v113, v112
	s_nop 1
	v_permlane16_swap_b32_e32 v113, v112
	s_waitcnt lgkmcnt(0)
	v_add_f32_e32 v112, v112, v113
	v_mov_b32_e32 v113, v112
	s_nop 1
	v_permlane32_swap_b32_e32 v113, v112
	s_and_saveexec_b64 s[60:61], s[42:43]
	s_mov_b32 s90, 0x8b00000
	s_cbranch_execz .LBB0_1411
	s_add_u32 s38, s75, s55
	s_addc_u32 s39, s76, s53
	s_waitcnt lgkmcnt(0)
	v_add_f32_e32 v114, v112, v113
	v_lshl_add_u64 v[112:113], v[166:167], 2, s[38:39]
	global_store_dword v[112:113], v114, off
; __device__ __forceinline__ unsigned cvt_pk_bf16(float lo, float hi) { unsigned r; asm volatile("v_cvt_pk_bf16_f32 %0, %1, %2" : "=v"(r) : "v"(lo), "v"(hi)); return r; }
; __device__ __forceinline__ float xlane_add(float v, int lane_, int mask) { return v + __uint_as_float((unsigned)__builtin_amdgcn_ds_bpermute((lane_ ^ mask) << 2, (int)__float_as_uint(v))); }
;     __device__ __forceinline__ void operator()(const f32x4 (&acc)[2][2][4][2], const Unit& u, int wr, int wc, int fr, int fq) const {
;     ...
;             for (int m = 0; m < 4; ++m) { float ss = 0.f; const int row = row0 + ai * HALF + m * 16;
; #pragma unroll
;                 for (int bj = 0; bj < 2; ++bj) { const u32x4 xw = xa[m][bj]; const f32x4 a0 = acc[ai][bj][m][0], a1 = acc[ai][bj][m][1];
;                     const float v0 = __uint_as_float(xw.x << 16) + a0[0] * alpha, v1 = __uint_as_float(xw.x & 0xffff0000u) + a0[1] * alpha, v2 = __uint_as_float(xw.y << 16) + a0[2] * alpha, v3 = __uint_as_float(xw.y & 0xffff0000u) + a0[3] * alpha;
;                     const float v4 = __uint_as_float(xw.z << 16) + a1[0] * alpha, v5 = __uint_as_float(xw.z & 0xffff0000u) + a1[1] * alpha, v6 = __uint_as_float(xw.w << 16) + a1[2] * alpha, v7 = __uint_as_float(xw.w & 0xffff0000u) + a1[3] * alpha;
;                     u32x4 w; w.x = cvt_pk_bf16(v0, v1); w.y = cvt_pk_bf16(v2, v3); w.z = cvt_pk_bf16(v4, v5); w.w = cvt_pk_bf16(v6, v7);
;                     *(__attribute__((address_space(1))) u32x4*)(D + (size_t)row * ldx + col0 + bj * HALF) = w;
;                     ss += (v0 * v0 + v1 * v1) + (v2 * v2 + v3 * v3) + (v4 * v4 + v5 * v5) + (v6 * v6 + v7 * v7); }
;                 ss = xlane_add(ss, lane_, 16); ss = xlane_add(ss, lane_, 32);
;                 if (fq == 0) ((__attribute__((address_space(1))) float*)ssq)[(size_t)slot * mrows + row] = ss; }
.LBB0_1411:
	s_or_b64 exec, exec, s[60:61]
	v_lshlrev_b32_e32 v114, 16, v148
	v_add_f32_e32 v108, v108, v114
	v_and_b32_e32 v114, 0xffff0000, v148
	v_add_f32_e32 v109, v109, v114
	v_lshlrev_b32_e32 v114, 16, v149
	v_add_f32_e32 v110, v110, v114
	v_and_b32_e32 v114, 0xffff0000, v149
	v_add_f32_e32 v111, v111, v114
	v_lshlrev_b32_e32 v114, 16, v150
	v_add_f32_e32 v114, v104, v114
	v_and_b32_e32 v104, 0xffff0000, v150
	v_add_f32_e32 v115, v105, v104
	v_lshlrev_b32_e32 v104, 16, v151
	v_add_f32_e32 v116, v106, v104
	v_and_b32_e32 v104, 0xffff0000, v151
	v_add_f32_e32 v117, v107, v104
	v_cvt_pk_bf16_f32 v104, v108, v109
	v_mul_f32_e32 v109, v109, v109
	v_fmac_f32_e32 v109, v108, v108
	v_mul_f32_e32 v108, v111, v111
	v_fmac_f32_e32 v108, v110, v110
	v_add_f32_e32 v108, v109, v108
	v_mul_f32_e32 v109, v115, v115
	v_fmac_f32_e32 v109, v114, v114
	v_add_f32_e32 v108, v109, v108
	v_mul_f32_e32 v109, v117, v117
	v_fmac_f32_e32 v109, v116, v116
	v_add_f32_e32 v108, v109, v108
	v_lshlrev_b32_e32 v109, 16, v144
	v_add_f32_e32 v100, v100, v109
	v_and_b32_e32 v109, 0xffff0000, v144
	v_add_f32_e32 v101, v101, v109
	v_lshlrev_b32_e32 v109, 16, v145
	v_add_f32_e32 v109, v102, v109
	v_and_b32_e32 v102, 0xffff0000, v145
	v_cvt_pk_bf16_f32 v105, v110, v111
	v_add_f32_e32 v110, v103, v102
	v_lshlrev_b32_e32 v102, 16, v146
	v_add_f32_e32 v111, v96, v102
	v_and_b32_e32 v96, 0xffff0000, v146
	v_cvt_pk_bf16_f32 v106, v114, v115
	v_add_f32_e32 v114, v97, v96
	v_lshlrev_b32_e32 v96, 16, v147
	v_add_f32_e32 v115, v98, v96
	v_and_b32_e32 v96, 0xffff0000, v147
	v_cvt_pk_bf16_f32 v107, v116, v117
	v_add_f32_e32 v116, v99, v96
	v_mul_f32_e32 v96, v101, v101
	v_mul_f32_e32 v97, v110, v110
	v_fmac_f32_e32 v96, v100, v100
	v_fmac_f32_e32 v97, v109, v109
	v_add_f32_e32 v96, v96, v97
	v_mul_f32_e32 v97, v114, v114
	v_fmac_f32_e32 v97, v111, v111
	v_add_f32_e32 v96, v97, v96
	v_mul_f32_e32 v97, v116, v116
	v_fmac_f32_e32 v97, v115, v115
	v_add_f32_e32 v96, v97, v96
	v_add_f32_e32 v99, v108, v96
	v_mov_b32_e32 v108, v99
	s_nop 1
	v_permlane16_swap_b32_e32 v108, v99
	s_waitcnt lgkmcnt(0)
	v_lshlrev_b64 v[112:113], 11, v[178:179]
	v_lshl_add_u64 v[96:97], v[112:113], 1, s[50:51]
	v_lshl_add_u64 v[102:103], v[168:169], 1, v[96:97]
	global_store_dwordx4 v[102:103], v[104:107], off
	s_waitcnt lgkmcnt(0)
	v_add_f32_e32 v96, v99, v108
	v_mov_b32_e32 v97, v96
	s_nop 1
	v_permlane32_swap_b32_e32 v97, v96
	v_cvt_pk_bf16_f32 v98, v100, v101
	v_cvt_pk_bf16_f32 v99, v109, v110
	v_cvt_pk_bf16_f32 v100, v111, v114
	v_cvt_pk_bf16_f32 v101, v115, v116
	global_store_dwordx4 v[102:103], v[98:101], off offset:256
	s_and_saveexec_b64 s[60:61], s[42:43]
	s_cbranch_execz .LBB0_1413
	s_add_u32 s38, s75, s55
	s_addc_u32 s39, s76, s53
	s_waitcnt lgkmcnt(0)
	v_add_f32_e32 v98, v96, v97
	v_lshl_add_u64 v[96:97], v[166:167], 2, s[38:39]
	global_store_dword v[96:97], v98, off offset:64
.LBB0_1413:
	s_or_b64 exec, exec, s[60:61]
	v_lshlrev_b32_e32 v98, 16, v140
	v_add_f32_e32 v92, v92, v98
	v_and_b32_e32 v98, 0xffff0000, v140
	v_add_f32_e32 v93, v93, v98
	v_lshlrev_b32_e32 v98, 16, v141
	v_add_f32_e32 v94, v94, v98
	v_and_b32_e32 v98, 0xffff0000, v141
	v_add_f32_e32 v95, v95, v98
	v_lshlrev_b32_e32 v98, 16, v142
	v_add_f32_e32 v98, v88, v98
	v_and_b32_e32 v88, 0xffff0000, v142
	v_add_f32_e32 v99, v89, v88
	v_lshlrev_b32_e32 v88, 16, v143
	v_add_f32_e32 v100, v90, v88
	v_and_b32_e32 v88, 0xffff0000, v143
	v_add_f32_e32 v101, v91, v88
	v_cvt_pk_bf16_f32 v88, v92, v93
	v_mul_f32_e32 v93, v93, v93
	v_fmac_f32_e32 v93, v92, v92
	v_mul_f32_e32 v92, v95, v95
	v_fmac_f32_e32 v92, v94, v94
	v_add_f32_e32 v92, v93, v92
	v_mul_f32_e32 v93, v99, v99
	v_fmac_f32_e32 v93, v98, v98
	v_add_f32_e32 v92, v93, v92
	v_mul_f32_e32 v93, v101, v101
	v_fmac_f32_e32 v93, v100, v100
	v_add_f32_e32 v92, v93, v92
	v_lshlrev_b32_e32 v93, 16, v132
	v_add_f32_e32 v84, v84, v93
	v_and_b32_e32 v93, 0xffff0000, v132
	v_add_f32_e32 v85, v85, v93
	v_lshlrev_b32_e32 v93, 16, v133
	v_add_f32_e32 v93, v86, v93
	v_and_b32_e32 v86, 0xffff0000, v133
	v_cvt_pk_bf16_f32 v89, v94, v95
	v_add_f32_e32 v94, v87, v86
	v_lshlrev_b32_e32 v86, 16, v134
	v_add_f32_e32 v95, v80, v86
	v_and_b32_e32 v80, 0xffff0000, v134
	v_cvt_pk_bf16_f32 v90, v98, v99
	v_add_f32_e32 v98, v81, v80
	v_lshlrev_b32_e32 v80, 16, v135
	v_add_f32_e32 v99, v82, v80
	v_and_b32_e32 v80, 0xffff0000, v135
	v_cvt_pk_bf16_f32 v91, v100, v101
	v_add_f32_e32 v100, v83, v80
	v_mul_f32_e32 v80, v85, v85
	v_mul_f32_e32 v81, v94, v94
	v_fmac_f32_e32 v80, v84, v84
	v_fmac_f32_e32 v81, v93, v93
	v_add_f32_e32 v80, v80, v81
	v_mul_f32_e32 v81, v98, v98
	v_fmac_f32_e32 v81, v95, v95
	v_add_f32_e32 v80, v81, v80
	v_mul_f32_e32 v81, v100, v100
	v_fmac_f32_e32 v81, v99, v99
	v_add_f32_e32 v80, v81, v80
	v_add_f32_e32 v83, v92, v80
	v_mov_b32_e32 v92, v83
	s_nop 1
	v_permlane16_swap_b32_e32 v92, v83
	s_waitcnt lgkmcnt(0)
	v_lshlrev_b64 v[96:97], 11, v[176:177]
	v_lshl_add_u64 v[80:81], v[96:97], 1, s[50:51]
	v_lshl_add_u64 v[86:87], v[168:169], 1, v[80:81]
	global_store_dwordx4 v[86:87], v[88:91], off
	s_waitcnt lgkmcnt(0)
	v_add_f32_e32 v80, v83, v92
	v_mov_b32_e32 v81, v80
	s_nop 1
	v_permlane32_swap_b32_e32 v81, v80
	v_cvt_pk_bf16_f32 v82, v84, v85
	v_cvt_pk_bf16_f32 v83, v93, v94
	v_cvt_pk_bf16_f32 v84, v95, v98
	v_cvt_pk_bf16_f32 v85, v99, v100
	global_store_dwordx4 v[86:87], v[82:85], off offset:256
	s_and_saveexec_b64 s[60:61], s[42:43]
	s_cbranch_execz .LBB0_1415
	s_add_u32 s38, s75, s55
	s_addc_u32 s39, s76, s53
	s_waitcnt lgkmcnt(0)
	v_add_f32_e32 v82, v80, v81
	v_lshl_add_u64 v[80:81], v[166:167], 2, s[38:39]
	global_store_dword v[80:81], v82, off offset:128
; __device__ __forceinline__ unsigned cvt_pk_bf16(float lo, float hi) { unsigned r; asm volatile("v_cvt_pk_bf16_f32 %0, %1, %2" : "=v"(r) : "v"(lo), "v"(hi)); return r; }
; __device__ __forceinline__ float xlane_add(float v, int lane_, int mask) { return v + __uint_as_float((unsigned)__builtin_amdgcn_ds_bpermute((lane_ ^ mask) << 2, (int)__float_as_uint(v))); }
;     __device__ __forceinline__ void operator()(const f32x4 (&acc)[2][2][4][2], const Unit& u, int wr, int wc, int fr, int fq) const {
;     ...
;         for (int ai = 0; ai < 2; ++ai) { u32x4 xa[4][2];
; #pragma unroll
;             for (int m = 0; m < 4; ++m)
; #pragma unroll
;                 for (int bj = 0; bj < 2; ++bj) xa[m][bj] = *(const __attribute__((address_space(1))) u32x4*)(S + (size_t)(row0 + ai * HALF + m * 16) * ldx + col0 + bj * HALF);
; #pragma unroll
;             for (int m = 0; m < 4; ++m) { float ss = 0.f; const int row = row0 + ai * HALF + m * 16;
; #pragma unroll
;                 for (int bj = 0; bj < 2; ++bj) { const u32x4 xw = xa[m][bj]; const f32x4 a0 = acc[ai][bj][m][0], a1 = acc[ai][bj][m][1];
;                     const float v0 = __uint_as_float(xw.x << 16) + a0[0] * alpha, v1 = __uint_as_float(xw.x & 0xffff0000u) + a0[1] * alpha, v2 = __uint_as_float(xw.y << 16) + a0[2] * alpha, v3 = __uint_as_float(xw.y & 0xffff0000u) + a0[3] * alpha;
;                     const float v4 = __uint_as_float(xw.z << 16) + a1[0] * alpha, v5 = __uint_as_float(xw.z & 0xffff0000u) + a1[1] * alpha, v6 = __uint_as_float(xw.w << 16) + a1[2] * alpha, v7 = __uint_as_float(xw.w & 0xffff0000u) + a1[3] * alpha;
;                     u32x4 w; w.x = cvt_pk_bf16(v0, v1); w.y = cvt_pk_bf16(v2, v3); w.z = cvt_pk_bf16(v4, v5); w.w = cvt_pk_bf16(v6, v7);
;                     *(__attribute__((address_space(1))) u32x4*)(D + (size_t)row * ldx + col0 + bj * HALF) = w;
;                     ss += (v0 * v0 + v1 * v1) + (v2 * v2 + v3 * v3) + (v4 * v4 + v5 * v5) + (v6 * v6 + v7 * v7); }
;                 ss = xlane_add(ss, lane_, 16); ss = xlane_add(ss, lane_, 32);
;                 if (fq == 0) ((__attribute__((address_space(1))) float*)ssq)[(size_t)slot * mrows + row] = ss; }
.LBB0_1415:
	s_or_b64 exec, exec, s[60:61]
	v_lshlrev_b32_e32 v82, 16, v136
	v_add_f32_e32 v76, v76, v82
	v_and_b32_e32 v82, 0xffff0000, v136
	v_add_f32_e32 v77, v77, v82
	v_lshlrev_b32_e32 v82, 16, v137
	v_add_f32_e32 v78, v78, v82
	v_and_b32_e32 v82, 0xffff0000, v137
	v_add_f32_e32 v79, v79, v82
	v_lshlrev_b32_e32 v82, 16, v138
	v_add_f32_e32 v82, v72, v82
	v_and_b32_e32 v72, 0xffff0000, v138
	v_add_f32_e32 v83, v73, v72
	v_lshlrev_b32_e32 v72, 16, v139
	v_add_f32_e32 v84, v74, v72
	v_and_b32_e32 v72, 0xffff0000, v139
	v_add_f32_e32 v85, v75, v72
	v_cvt_pk_bf16_f32 v72, v76, v77
	v_mul_f32_e32 v77, v77, v77
	v_fmac_f32_e32 v77, v76, v76
	v_mul_f32_e32 v76, v79, v79
	v_fmac_f32_e32 v76, v78, v78
	v_add_f32_e32 v76, v77, v76
	v_mul_f32_e32 v77, v83, v83
	v_fmac_f32_e32 v77, v82, v82
	v_add_f32_e32 v76, v77, v76
	v_mul_f32_e32 v77, v85, v85
	v_fmac_f32_e32 v77, v84, v84
	v_add_f32_e32 v76, v77, v76
	v_lshlrev_b32_e32 v77, 16, v128
	v_add_f32_e32 v68, v68, v77
	v_and_b32_e32 v77, 0xffff0000, v128
	v_add_f32_e32 v69, v69, v77
	v_lshlrev_b32_e32 v77, 16, v129
	v_add_f32_e32 v77, v70, v77
	v_and_b32_e32 v70, 0xffff0000, v129
	v_cvt_pk_bf16_f32 v73, v78, v79
	v_add_f32_e32 v78, v71, v70
	v_lshlrev_b32_e32 v70, 16, v130
	v_add_f32_e32 v79, v64, v70
	v_and_b32_e32 v64, 0xffff0000, v130
	v_cvt_pk_bf16_f32 v74, v82, v83
	v_add_f32_e32 v82, v65, v64
	v_lshlrev_b32_e32 v64, 16, v131
	v_add_f32_e32 v83, v66, v64
	v_and_b32_e32 v64, 0xffff0000, v131
	v_cvt_pk_bf16_f32 v75, v84, v85
	v_add_f32_e32 v84, v67, v64
	v_mul_f32_e32 v64, v69, v69
	v_mul_f32_e32 v65, v78, v78
	v_fmac_f32_e32 v64, v68, v68
	v_fmac_f32_e32 v65, v77, v77
	v_add_f32_e32 v64, v64, v65
	v_mul_f32_e32 v65, v82, v82
	v_fmac_f32_e32 v65, v79, v79
	v_add_f32_e32 v64, v65, v64
	v_mul_f32_e32 v65, v84, v84
	v_fmac_f32_e32 v65, v83, v83
	v_add_f32_e32 v64, v65, v64
	v_add_f32_e32 v67, v76, v64
	v_mov_b32_e32 v76, v67
	s_nop 1
	v_permlane16_swap_b32_e32 v76, v67
	s_waitcnt lgkmcnt(0)
	v_lshlrev_b64 v[80:81], 11, v[174:175]
	v_lshl_add_u64 v[64:65], v[80:81], 1, s[50:51]
	v_lshl_add_u64 v[70:71], v[168:169], 1, v[64:65]
	global_store_dwordx4 v[70:71], v[72:75], off
	s_waitcnt lgkmcnt(0)
	v_add_f32_e32 v64, v67, v76
	v_mov_b32_e32 v65, v64
	s_nop 1
	v_permlane32_swap_b32_e32 v65, v64
	v_cvt_pk_bf16_f32 v66, v68, v69
	v_cvt_pk_bf16_f32 v67, v77, v78
	v_cvt_pk_bf16_f32 v68, v79, v82
	v_cvt_pk_bf16_f32 v69, v83, v84
	global_store_dwordx4 v[70:71], v[66:69], off offset:256
	s_and_saveexec_b64 s[60:61], s[42:43]
	s_cbranch_execz .LBB0_1417
	s_add_u32 s38, s75, s55
	s_addc_u32 s39, s76, s53
	s_waitcnt lgkmcnt(0)
	v_add_f32_e32 v66, v64, v65
	v_lshl_add_u64 v[64:65], v[166:167], 2, s[38:39]
	global_store_dword v[64:65], v66, off offset:192
.LBB0_1417:
	s_or_b64 exec, exec, s[60:61]
	s_mov_b64 s[38:39], 0x80000
	v_lshl_add_u64 v[102:103], v[172:173], 0, s[38:39]
	s_waitcnt lgkmcnt(0)
	v_lshl_add_u64 v[64:65], v[170:171], 0, v[102:103]
	global_load_dwordx4 v[98:101], v[64:65], off
	global_load_dwordx4 v[88:91], v[64:65], off offset:256
	v_add_u32_e32 v96, 0x90, v166
	v_ashrrev_i32_e32 v97, 31, v96
	v_lshlrev_b64 v[64:65], 12, v[96:97]
	v_add_u32_e32 v94, 0xa0, v166
	v_lshl_add_u64 v[64:65], v[170:171], 0, v[64:65]
	v_ashrrev_i32_e32 v95, 31, v94
	global_load_dwordx4 v[84:87], v[64:65], off
	global_load_dwordx4 v[80:83], v[64:65], off offset:256
	v_lshlrev_b64 v[64:65], 12, v[94:95]
	v_add_u32_e32 v92, 0xb0, v166
	v_lshl_add_u64 v[64:65], v[170:171], 0, v[64:65]
	v_ashrrev_i32_e32 v93, 31, v92
	global_load_dwordx4 v[76:79], v[64:65], off
	global_load_dwordx4 v[68:71], v[64:65], off offset:256
	v_lshlrev_b64 v[64:65], 12, v[92:93]
	v_lshl_add_u64 v[64:65], v[170:171], 0, v[64:65]
	global_load_dwordx4 v[72:75], v[64:65], off
	s_nop 0
	global_load_dwordx4 v[64:67], v[64:65], off offset:256
	s_waitcnt vmcnt(7)
	v_lshlrev_b32_e32 v104, 16, v98
	v_add_f32_e32 v104, v60, v104
	v_and_b32_e32 v60, 0xffff0000, v98
	v_add_f32_e32 v98, v61, v60
	v_lshlrev_b32_e32 v60, 16, v99
	v_add_f32_e32 v62, v62, v60
	v_and_b32_e32 v60, 0xffff0000, v99
	v_add_f32_e32 v63, v63, v60
	v_lshlrev_b32_e32 v60, 16, v100
	v_add_f32_e32 v99, v56, v60
	v_and_b32_e32 v56, 0xffff0000, v100
	v_add_f32_e32 v100, v57, v56
	v_lshlrev_b32_e32 v56, 16, v101
	v_add_f32_e32 v105, v58, v56
	v_and_b32_e32 v56, 0xffff0000, v101
	v_lshl_add_u64 v[60:61], s[50:51], 0, v[102:103]
	v_add_f32_e32 v101, v59, v56
	v_cvt_pk_bf16_f32 v56, v104, v98
	v_cvt_pk_bf16_f32 v57, v62, v63
	v_lshl_add_u64 v[60:61], v[168:169], 1, v[60:61]
	v_cvt_pk_bf16_f32 v58, v99, v100
	v_cvt_pk_bf16_f32 v59, v105, v101
	global_store_dwordx4 v[60:61], v[56:59], off
	s_nop 1
	v_mul_f32_e32 v56, v98, v98
	v_mul_f32_e32 v57, v63, v63
	v_fmac_f32_e32 v56, v104, v104
	v_fmac_f32_e32 v57, v62, v62
	v_add_f32_e32 v56, v56, v57
	v_mul_f32_e32 v57, v100, v100
	v_fmac_f32_e32 v57, v99, v99
	v_add_f32_e32 v56, v57, v56
	v_mul_f32_e32 v57, v101, v101
	v_fmac_f32_e32 v57, v105, v105
	v_add_f32_e32 v56, v57, v56
	s_waitcnt vmcnt(7)
	v_lshlrev_b32_e32 v57, 16, v88
	v_add_f32_e32 v52, v52, v57
	v_and_b32_e32 v57, 0xffff0000, v88
	v_add_f32_e32 v53, v53, v57
	v_lshlrev_b32_e32 v57, 16, v89
	v_add_f32_e32 v54, v54, v57
	v_and_b32_e32 v57, 0xffff0000, v89
	v_add_f32_e32 v55, v55, v57
	v_lshlrev_b32_e32 v57, 16, v90
	v_add_f32_e32 v57, v48, v57
	v_and_b32_e32 v48, 0xffff0000, v90
	v_add_f32_e32 v58, v49, v48
	v_lshlrev_b32_e32 v48, 16, v91
	v_add_f32_e32 v59, v50, v48
	v_and_b32_e32 v48, 0xffff0000, v91
	v_add_f32_e32 v62, v51, v48
	v_cvt_pk_bf16_f32 v48, v52, v53
	v_cvt_pk_bf16_f32 v49, v54, v55
	v_cvt_pk_bf16_f32 v50, v57, v58
	v_cvt_pk_bf16_f32 v51, v59, v62
	global_store_dwordx4 v[60:61], v[48:51], off offset:256
	s_nop 1
	v_mul_f32_e32 v48, v53, v53
	v_mul_f32_e32 v49, v55, v55
	v_fmac_f32_e32 v48, v52, v52
	v_fmac_f32_e32 v49, v54, v54
	v_add_f32_e32 v48, v48, v49
	v_mul_f32_e32 v49, v58, v58
	v_fmac_f32_e32 v49, v57, v57
	v_add_f32_e32 v48, v49, v48
	v_mul_f32_e32 v49, v62, v62
	v_fmac_f32_e32 v49, v59, v59
	v_add_f32_e32 v48, v49, v48
	v_add_f32_e32 v48, v56, v48
	v_mov_b32_e32 v49, v48
	s_nop 1
	v_permlane16_swap_b32_e32 v49, v48
	s_waitcnt lgkmcnt(0)
	v_add_f32_e32 v48, v48, v49
	v_mov_b32_e32 v49, v48
	s_nop 1
	v_permlane32_swap_b32_e32 v49, v48
	s_and_saveexec_b64 s[60:61], s[42:43]
	s_cbranch_execz .LBB0_1419
	s_add_u32 s38, s75, s55
	s_addc_u32 s39, s76, s53
	s_waitcnt lgkmcnt(0)
	v_add_f32_e32 v50, v48, v49
	v_lshl_add_u64 v[48:49], v[166:167], 2, s[38:39]
	global_store_dword v[48:49], v50, off offset:512
; __device__ __forceinline__ unsigned cvt_pk_bf16(float lo, float hi) { unsigned r; asm volatile("v_cvt_pk_bf16_f32 %0, %1, %2" : "=v"(r) : "v"(lo), "v"(hi)); return r; }
; __device__ __forceinline__ float xlane_add(float v, int lane_, int mask) { return v + __uint_as_float((unsigned)__builtin_amdgcn_ds_bpermute((lane_ ^ mask) << 2, (int)__float_as_uint(v))); }
;     __device__ __forceinline__ void operator()(const f32x4 (&acc)[2][2][4][2], const Unit& u, int wr, int wc, int fr, int fq) const {
;     ...
;             for (int m = 0; m < 4; ++m) { float ss = 0.f; const int row = row0 + ai * HALF + m * 16;
; #pragma unroll
;                 for (int bj = 0; bj < 2; ++bj) { const u32x4 xw = xa[m][bj]; const f32x4 a0 = acc[ai][bj][m][0], a1 = acc[ai][bj][m][1];
;                     const float v0 = __uint_as_float(xw.x << 16) + a0[0] * alpha, v1 = __uint_as_float(xw.x & 0xffff0000u) + a0[1] * alpha, v2 = __uint_as_float(xw.y << 16) + a0[2] * alpha, v3 = __uint_as_float(xw.y & 0xffff0000u) + a0[3] * alpha;
;                     const float v4 = __uint_as_float(xw.z << 16) + a1[0] * alpha, v5 = __uint_as_float(xw.z & 0xffff0000u) + a1[1] * alpha, v6 = __uint_as_float(xw.w << 16) + a1[2] * alpha, v7 = __uint_as_float(xw.w & 0xffff0000u) + a1[3] * alpha;
;                     u32x4 w; w.x = cvt_pk_bf16(v0, v1); w.y = cvt_pk_bf16(v2, v3); w.z = cvt_pk_bf16(v4, v5); w.w = cvt_pk_bf16(v6, v7);
;                     *(__attribute__((address_space(1))) u32x4*)(D + (size_t)row * ldx + col0 + bj * HALF) = w;
;                     ss += (v0 * v0 + v1 * v1) + (v2 * v2 + v3 * v3) + (v4 * v4 + v5 * v5) + (v6 * v6 + v7 * v7); }
;                 ss = xlane_add(ss, lane_, 16); ss = xlane_add(ss, lane_, 32);
;                 if (fq == 0) ((__attribute__((address_space(1))) float*)ssq)[(size_t)slot * mrows + row] = ss; }
.LBB0_1419:
	s_or_b64 exec, exec, s[60:61]
	s_waitcnt vmcnt(7)
	v_lshlrev_b32_e32 v50, 16, v84
	v_add_f32_e32 v44, v44, v50
	v_and_b32_e32 v50, 0xffff0000, v84
	v_add_f32_e32 v45, v45, v50
	v_lshlrev_b32_e32 v50, 16, v85
	v_add_f32_e32 v46, v46, v50
	v_and_b32_e32 v50, 0xffff0000, v85
	v_add_f32_e32 v47, v47, v50
	v_lshlrev_b32_e32 v50, 16, v86
	v_add_f32_e32 v50, v40, v50
	v_and_b32_e32 v40, 0xffff0000, v86
	v_add_f32_e32 v51, v41, v40
	v_lshlrev_b32_e32 v40, 16, v87
	v_add_f32_e32 v52, v42, v40
	v_and_b32_e32 v40, 0xffff0000, v87
	v_add_f32_e32 v53, v43, v40
	v_cvt_pk_bf16_f32 v40, v44, v45
	v_mul_f32_e32 v45, v45, v45
	v_fmac_f32_e32 v45, v44, v44
	v_mul_f32_e32 v44, v47, v47
	v_fmac_f32_e32 v44, v46, v46
	v_add_f32_e32 v44, v45, v44
	v_mul_f32_e32 v45, v51, v51
	v_fmac_f32_e32 v45, v50, v50
	v_add_f32_e32 v44, v45, v44
	v_mul_f32_e32 v45, v53, v53
	v_fmac_f32_e32 v45, v52, v52
	v_add_f32_e32 v44, v45, v44
	s_waitcnt vmcnt(6)
	v_lshlrev_b32_e32 v45, 16, v80
	v_add_f32_e32 v36, v36, v45
	v_and_b32_e32 v45, 0xffff0000, v80
	v_add_f32_e32 v37, v37, v45
	v_lshlrev_b32_e32 v45, 16, v81
	v_add_f32_e32 v45, v38, v45
	v_and_b32_e32 v38, 0xffff0000, v81
	v_cvt_pk_bf16_f32 v41, v46, v47
	v_add_f32_e32 v46, v39, v38
	v_lshlrev_b32_e32 v38, 16, v82
	v_add_f32_e32 v47, v32, v38
	v_and_b32_e32 v32, 0xffff0000, v82
	v_cvt_pk_bf16_f32 v42, v50, v51
	v_add_f32_e32 v50, v33, v32
	v_lshlrev_b32_e32 v32, 16, v83
	v_add_f32_e32 v51, v34, v32
	v_and_b32_e32 v32, 0xffff0000, v83
	v_cvt_pk_bf16_f32 v43, v52, v53
	v_add_f32_e32 v52, v35, v32
	v_mul_f32_e32 v32, v37, v37
	v_mul_f32_e32 v33, v46, v46
	v_fmac_f32_e32 v32, v36, v36
	v_fmac_f32_e32 v33, v45, v45
	v_add_f32_e32 v32, v32, v33
	v_mul_f32_e32 v33, v50, v50
	v_fmac_f32_e32 v33, v47, v47
	v_add_f32_e32 v32, v33, v32
	v_mul_f32_e32 v33, v52, v52
	v_fmac_f32_e32 v33, v51, v51
	v_add_f32_e32 v32, v33, v32
	v_add_f32_e32 v35, v44, v32
	v_mov_b32_e32 v44, v35
	s_nop 1
	v_permlane16_swap_b32_e32 v44, v35
	s_waitcnt lgkmcnt(0)
	v_lshlrev_b64 v[48:49], 11, v[96:97]
	v_lshl_add_u64 v[32:33], v[48:49], 1, s[50:51]
	v_lshl_add_u64 v[38:39], v[168:169], 1, v[32:33]
	global_store_dwordx4 v[38:39], v[40:43], off
	s_waitcnt lgkmcnt(0)
	v_add_f32_e32 v32, v35, v44
	v_mov_b32_e32 v33, v32
	s_nop 1
	v_permlane32_swap_b32_e32 v33, v32
	v_cvt_pk_bf16_f32 v34, v36, v37
	v_cvt_pk_bf16_f32 v35, v45, v46
	v_cvt_pk_bf16_f32 v36, v47, v50
	v_cvt_pk_bf16_f32 v37, v51, v52
	global_store_dwordx4 v[38:39], v[34:37], off offset:256
	s_and_saveexec_b64 s[60:61], s[42:43]
	s_cbranch_execz .LBB0_1421
	s_add_u32 s38, s75, s55
	s_addc_u32 s39, s76, s53
	s_waitcnt lgkmcnt(0)
	v_add_f32_e32 v34, v32, v33
	v_lshl_add_u64 v[32:33], v[166:167], 2, s[38:39]
	global_store_dword v[32:33], v34, off offset:576
; __device__ __forceinline__ unsigned cvt_pk_bf16(float lo, float hi) { unsigned r; asm volatile("v_cvt_pk_bf16_f32 %0, %1, %2" : "=v"(r) : "v"(lo), "v"(hi)); return r; }
; __device__ __forceinline__ float xlane_add(float v, int lane_, int mask) { return v + __uint_as_float((unsigned)__builtin_amdgcn_ds_bpermute((lane_ ^ mask) << 2, (int)__float_as_uint(v))); }
;     __device__ __forceinline__ void operator()(const f32x4 (&acc)[2][2][4][2], const Unit& u, int wr, int wc, int fr, int fq) const {
;     ...
;             for (int m = 0; m < 4; ++m) { float ss = 0.f; const int row = row0 + ai * HALF + m * 16;
; #pragma unroll
;                 for (int bj = 0; bj < 2; ++bj) { const u32x4 xw = xa[m][bj]; const f32x4 a0 = acc[ai][bj][m][0], a1 = acc[ai][bj][m][1];
;                     const float v0 = __uint_as_float(xw.x << 16) + a0[0] * alpha, v1 = __uint_as_float(xw.x & 0xffff0000u) + a0[1] * alpha, v2 = __uint_as_float(xw.y << 16) + a0[2] * alpha, v3 = __uint_as_float(xw.y & 0xffff0000u) + a0[3] * alpha;
;                     const float v4 = __uint_as_float(xw.z << 16) + a1[0] * alpha, v5 = __uint_as_float(xw.z & 0xffff0000u) + a1[1] * alpha, v6 = __uint_as_float(xw.w << 16) + a1[2] * alpha, v7 = __uint_as_float(xw.w & 0xffff0000u) + a1[3] * alpha;
;                     u32x4 w; w.x = cvt_pk_bf16(v0, v1); w.y = cvt_pk_bf16(v2, v3); w.z = cvt_pk_bf16(v4, v5); w.w = cvt_pk_bf16(v6, v7);
;                     *(__attribute__((address_space(1))) u32x4*)(D + (size_t)row * ldx + col0 + bj * HALF) = w;
;                     ss += (v0 * v0 + v1 * v1) + (v2 * v2 + v3 * v3) + (v4 * v4 + v5 * v5) + (v6 * v6 + v7 * v7); }
;                 ss = xlane_add(ss, lane_, 16); ss = xlane_add(ss, lane_, 32);
;                 if (fq == 0) ((__attribute__((address_space(1))) float*)ssq)[(size_t)slot * mrows + row] = ss; }
.LBB0_1421:
	s_or_b64 exec, exec, s[60:61]
	s_waitcnt vmcnt(7)
	v_lshlrev_b32_e32 v34, 16, v76
	v_add_f32_e32 v28, v28, v34
	v_and_b32_e32 v34, 0xffff0000, v76
	v_add_f32_e32 v29, v29, v34
	v_lshlrev_b32_e32 v34, 16, v77
	v_add_f32_e32 v30, v30, v34
	v_and_b32_e32 v34, 0xffff0000, v77
	v_add_f32_e32 v31, v31, v34
	v_lshlrev_b32_e32 v34, 16, v78
	v_add_f32_e32 v34, v24, v34
	v_and_b32_e32 v24, 0xffff0000, v78
	v_add_f32_e32 v35, v25, v24
	v_lshlrev_b32_e32 v24, 16, v79
	v_add_f32_e32 v36, v26, v24
	v_and_b32_e32 v24, 0xffff0000, v79
	v_add_f32_e32 v37, v27, v24
	v_cvt_pk_bf16_f32 v24, v28, v29
	v_mul_f32_e32 v29, v29, v29
	v_fmac_f32_e32 v29, v28, v28
	v_mul_f32_e32 v28, v31, v31
	v_fmac_f32_e32 v28, v30, v30
	v_add_f32_e32 v28, v29, v28
	v_mul_f32_e32 v29, v35, v35
	v_fmac_f32_e32 v29, v34, v34
	v_add_f32_e32 v28, v29, v28
	v_mul_f32_e32 v29, v37, v37
	v_fmac_f32_e32 v29, v36, v36
	v_add_f32_e32 v28, v29, v28
	s_waitcnt vmcnt(6)
	v_lshlrev_b32_e32 v29, 16, v68
	v_add_f32_e32 v20, v20, v29
	v_and_b32_e32 v29, 0xffff0000, v68
	v_add_f32_e32 v21, v21, v29
	v_lshlrev_b32_e32 v29, 16, v69
	v_add_f32_e32 v29, v22, v29
	v_and_b32_e32 v22, 0xffff0000, v69
	v_cvt_pk_bf16_f32 v25, v30, v31
	v_add_f32_e32 v30, v23, v22
	v_lshlrev_b32_e32 v22, 16, v70
	v_add_f32_e32 v31, v16, v22
	v_and_b32_e32 v16, 0xffff0000, v70
	v_cvt_pk_bf16_f32 v26, v34, v35
	v_add_f32_e32 v34, v17, v16
	v_lshlrev_b32_e32 v16, 16, v71
	v_add_f32_e32 v35, v18, v16
	v_and_b32_e32 v16, 0xffff0000, v71
	v_cvt_pk_bf16_f32 v27, v36, v37
	v_add_f32_e32 v36, v19, v16
	v_mul_f32_e32 v16, v21, v21
	v_mul_f32_e32 v17, v30, v30
	v_fmac_f32_e32 v16, v20, v20
	v_fmac_f32_e32 v17, v29, v29
	v_add_f32_e32 v16, v16, v17
	v_mul_f32_e32 v17, v34, v34
	v_fmac_f32_e32 v17, v31, v31
	v_add_f32_e32 v16, v17, v16
	v_mul_f32_e32 v17, v36, v36
	v_fmac_f32_e32 v17, v35, v35
	v_add_f32_e32 v16, v17, v16
	v_add_f32_e32 v19, v28, v16
	v_mov_b32_e32 v28, v19
	s_nop 1
	v_permlane16_swap_b32_e32 v28, v19
	s_waitcnt lgkmcnt(0)
	v_lshlrev_b64 v[32:33], 11, v[94:95]
	v_lshl_add_u64 v[16:17], v[32:33], 1, s[50:51]
	v_lshl_add_u64 v[22:23], v[168:169], 1, v[16:17]
	global_store_dwordx4 v[22:23], v[24:27], off
	s_waitcnt lgkmcnt(0)
	v_add_f32_e32 v16, v19, v28
	v_mov_b32_e32 v17, v16
	s_nop 1
	v_permlane32_swap_b32_e32 v17, v16
	v_cvt_pk_bf16_f32 v18, v20, v21
	v_cvt_pk_bf16_f32 v19, v29, v30
	v_cvt_pk_bf16_f32 v20, v31, v34
	v_cvt_pk_bf16_f32 v21, v35, v36
	global_store_dwordx4 v[22:23], v[18:21], off offset:256
	s_and_saveexec_b64 s[60:61], s[42:43]
	s_cbranch_execz .LBB0_1423
	s_add_u32 s38, s75, s55
	s_addc_u32 s39, s76, s53
	s_waitcnt lgkmcnt(0)
	v_add_f32_e32 v18, v16, v17
	v_lshl_add_u64 v[16:17], v[166:167], 2, s[38:39]
	global_store_dword v[16:17], v18, off offset:640
.LBB0_1423:
	s_or_b64 exec, exec, s[60:61]
	s_waitcnt vmcnt(7)
	v_lshlrev_b32_e32 v18, 16, v72
	v_add_f32_e32 v12, v12, v18
	v_and_b32_e32 v18, 0xffff0000, v72
	v_add_f32_e32 v13, v13, v18
	v_lshlrev_b32_e32 v18, 16, v73
	v_add_f32_e32 v14, v14, v18
	v_and_b32_e32 v18, 0xffff0000, v73
	v_add_f32_e32 v15, v15, v18
	v_lshlrev_b32_e32 v18, 16, v74
	v_add_f32_e32 v18, v8, v18
	v_and_b32_e32 v8, 0xffff0000, v74
	v_add_f32_e32 v19, v9, v8
	v_lshlrev_b32_e32 v8, 16, v75
	v_add_f32_e32 v20, v10, v8
	v_and_b32_e32 v8, 0xffff0000, v75
	v_add_f32_e32 v21, v11, v8
	v_cvt_pk_bf16_f32 v8, v12, v13
	v_mul_f32_e32 v13, v13, v13
	v_fmac_f32_e32 v13, v12, v12
	v_mul_f32_e32 v12, v15, v15
	v_fmac_f32_e32 v12, v14, v14
	v_add_f32_e32 v12, v13, v12
	v_mul_f32_e32 v13, v19, v19
	v_fmac_f32_e32 v13, v18, v18
	v_add_f32_e32 v12, v13, v12
	v_mul_f32_e32 v13, v21, v21
	v_fmac_f32_e32 v13, v20, v20
	v_add_f32_e32 v12, v13, v12
	s_waitcnt vmcnt(6)
	v_lshlrev_b32_e32 v13, 16, v64
	v_add_f32_e32 v4, v4, v13
	v_and_b32_e32 v13, 0xffff0000, v64
	v_add_f32_e32 v5, v5, v13
	v_lshlrev_b32_e32 v13, 16, v65
	v_add_f32_e32 v13, v6, v13
	v_and_b32_e32 v6, 0xffff0000, v65
	v_cvt_pk_bf16_f32 v9, v14, v15
	v_add_f32_e32 v14, v7, v6
	v_lshlrev_b32_e32 v6, 16, v66
	v_add_f32_e32 v15, v0, v6
	v_and_b32_e32 v0, 0xffff0000, v66
	v_cvt_pk_bf16_f32 v10, v18, v19
	v_add_f32_e32 v18, v1, v0
	v_lshlrev_b32_e32 v0, 16, v67
	v_add_f32_e32 v19, v2, v0
	v_and_b32_e32 v0, 0xffff0000, v67
	v_cvt_pk_bf16_f32 v11, v20, v21
	v_add_f32_e32 v20, v3, v0
	v_mul_f32_e32 v0, v5, v5
	v_mul_f32_e32 v1, v14, v14
	v_fmac_f32_e32 v0, v4, v4
	v_fmac_f32_e32 v1, v13, v13
	v_add_f32_e32 v0, v0, v1
	v_mul_f32_e32 v1, v18, v18
	v_fmac_f32_e32 v1, v15, v15
	v_add_f32_e32 v0, v1, v0
	v_mul_f32_e32 v1, v20, v20
	v_fmac_f32_e32 v1, v19, v19
	v_add_f32_e32 v0, v1, v0
	v_add_f32_e32 v3, v12, v0
	v_mov_b32_e32 v12, v3
	s_nop 1
	v_permlane16_swap_b32_e32 v12, v3
	s_waitcnt lgkmcnt(0)
	v_lshlrev_b64 v[16:17], 11, v[92:93]
	v_lshl_add_u64 v[0:1], v[16:17], 1, s[50:51]
	v_lshl_add_u64 v[6:7], v[168:169], 1, v[0:1]
	global_store_dwordx4 v[6:7], v[8:11], off
	s_waitcnt lgkmcnt(0)
	v_add_f32_e32 v0, v3, v12
	v_mov_b32_e32 v1, v0
	s_nop 1
	v_permlane32_swap_b32_e32 v1, v0
	v_cvt_pk_bf16_f32 v2, v4, v5
	v_cvt_pk_bf16_f32 v3, v13, v14
	v_cvt_pk_bf16_f32 v4, v15, v18
	v_cvt_pk_bf16_f32 v5, v19, v20
	global_store_dwordx4 v[6:7], v[2:5], off offset:256
	s_and_saveexec_b64 s[60:61], s[42:43]
	s_cbranch_execz .LBB0_1425
	s_add_u32 s38, s75, s55
	s_addc_u32 s39, s76, s53
	s_waitcnt lgkmcnt(0)
	v_add_f32_e32 v2, v0, v1
	v_lshl_add_u64 v[0:1], v[166:167], 2, s[38:39]
	global_store_dword v[0:1], v2, off offset:704

; __device__ __forceinline__ unsigned cvt_pk_bf16(float lo, float hi) { unsigned r; asm volatile("v_cvt_pk_bf16_f32 %0, %1, %2" : "=v"(r) : "v"(lo), "v"(hi)); return r; }
; __device__ __forceinline__ float xlane_add(float v, int lane_, int mask) { return v + __uint_as_float((unsigned)__builtin_amdgcn_ds_bpermute((lane_ ^ mask) << 2, (int)__float_as_uint(v))); }
;     __device__ __forceinline__ void operator()(const f32x4 (&acc)[2][2][4][2], const Unit& u, int wr, int wc, int fr, int fq) const {
;     ...
;         for (int ai = 0; ai < 2; ++ai) { u32x4 xa[4][2];
; #pragma unroll
;             for (int m = 0; m < 4; ++m)
; #pragma unroll
;                 for (int bj = 0; bj < 2; ++bj) xa[m][bj] = *(const __attribute__((address_space(1))) u32x4*)(S + (size_t)(row0 + ai * HALF + m * 16) * ldx + col0 + bj * HALF);
; #pragma unroll
;             for (int m = 0; m < 4; ++m) { float ss = 0.f; const int row = row0 + ai * HALF + m * 16;
; #pragma unroll
;                 for (int bj = 0; bj < 2; ++bj) { const u32x4 xw = xa[m][bj]; const f32x4 a0 = acc[ai][bj][m][0], a1 = acc[ai][bj][m][1];
;                     const float v0 = __uint_as_float(xw.x << 16) + a0[0] * alpha, v1 = __uint_as_float(xw.x & 0xffff0000u) + a0[1] * alpha, v2 = __uint_as_float(xw.y << 16) + a0[2] * alpha, v3 = __uint_as_float(xw.y & 0xffff0000u) + a0[3] * alpha;
;                     const float v4 = __uint_as_float(xw.z << 16) + a1[0] * alpha, v5 = __uint_as_float(xw.z & 0xffff0000u) + a1[1] * alpha, v6 = __uint_as_float(xw.w << 16) + a1[2] * alpha, v7 = __uint_as_float(xw.w & 0xffff0000u) + a1[3] * alpha;
;                     u32x4 w; w.x = cvt_pk_bf16(v0, v1); w.y = cvt_pk_bf16(v2, v3); w.z = cvt_pk_bf16(v4, v5); w.w = cvt_pk_bf16(v6, v7);
;                     *(__attribute__((address_space(1))) u32x4*)(D + (size_t)row * ldx + col0 + bj * HALF) = w;
;                     ss += (v0 * v0 + v1 * v1) + (v2 * v2 + v3 * v3) + (v4 * v4 + v5 * v5) + (v6 * v6 + v7 * v7); }
;                 ss = xlane_add(ss, lane_, 16); ss = xlane_add(ss, lane_, 32);
;                 if (fq == 0) ((__attribute__((address_space(1))) float*)ssq)[(size_t)slot * mrows + row] = ss; }
.LBB0_1756:
	v_lshl_or_b32 v168, s82, 8, v182
	v_lshl_add_u32 v166, s83, 8, v180
	v_ashrrev_i32_e32 v169, 31, v168
	v_lshlrev_b64 v[190:191], 1, v[168:169]
	v_ashrrev_i32_e32 v167, 31, v166
	v_lshl_add_u64 v[170:171], s[46:47], 0, v[190:191]
	v_lshlrev_b64 v[172:173], 12, v[166:167]
	v_lshl_add_u64 v[120:121], v[170:171], 0, v[172:173]
	global_load_dwordx4 v[186:189], v[120:121], off
	global_load_dwordx4 v[152:155], v[120:121], off offset:256
	v_or_b32_e32 v178, 16, v166
	v_ashrrev_i32_e32 v179, 31, v178
	v_lshlrev_b64 v[120:121], 12, v[178:179]
	v_or_b32_e32 v176, 32, v166
	v_lshl_add_u64 v[120:121], v[170:171], 0, v[120:121]
	v_ashrrev_i32_e32 v177, 31, v176
	global_load_dwordx4 v[148:151], v[120:121], off
	global_load_dwordx4 v[144:147], v[120:121], off offset:256
	v_lshlrev_b64 v[120:121], 12, v[176:177]
	v_or_b32_e32 v174, 48, v166
	v_lshl_add_u64 v[120:121], v[170:171], 0, v[120:121]
	v_ashrrev_i32_e32 v175, 31, v174
	global_load_dwordx4 v[140:143], v[120:121], off
	global_load_dwordx4 v[136:139], v[120:121], off offset:256
	v_lshlrev_b64 v[120:121], 12, v[174:175]
	v_lshl_add_u64 v[120:121], v[170:171], 0, v[120:121]
	global_load_dwordx4 v[132:135], v[120:121], off
	s_nop 0
	global_load_dwordx4 v[120:123], v[120:121], off offset:256
	s_lshl_b32 s54, s82, 2
	s_or_b32 s57, s54, s73
	s_mul_hi_i32 s56, s57, 0x28000
	s_mul_i32 s57, s57, 0x28000
	s_waitcnt vmcnt(0)
	v_lshlrev_b32_e32 v193, 16, v187
	v_lshlrev_b32_e32 v192, 16, v186
	v_and_b32_e32 v186, 0xffff0000, v186
	v_fmac_f32_e32 v193, 0.5, v130
	v_and_b32_e32 v130, 0xffff0000, v187
	v_fmac_f32_e32 v192, 0.5, v128
	v_fmac_f32_e32 v186, 0.5, v129
	v_fmac_f32_e32 v130, 0.5, v131
	v_lshlrev_b32_e32 v131, 16, v188
	v_and_b32_e32 v187, 0xffff0000, v188
	v_lshl_add_u64 v[128:129], s[48:49], 0, v[172:173]
	v_fmac_f32_e32 v131, 0.5, v124
	v_fmac_f32_e32 v187, 0.5, v125
	v_lshlrev_b32_e32 v188, 16, v189
	v_and_b32_e32 v189, 0xffff0000, v189
	v_cvt_pk_bf16_f32 v124, v192, v186
	v_cvt_pk_bf16_f32 v125, v193, v130
	v_lshl_add_u64 v[128:129], v[128:129], 0, v[190:191]
	v_fmac_f32_e32 v188, 0.5, v126
	v_fmac_f32_e32 v189, 0.5, v127
	v_cvt_pk_bf16_f32 v126, v131, v187
	v_cvt_pk_bf16_f32 v127, v188, v189
	global_store_dwordx4 v[128:129], v[124:127], off
	s_nop 1
	v_mul_f32_e32 v124, v186, v186
	v_mul_f32_e32 v125, v130, v130
	v_fmac_f32_e32 v124, v192, v192
	v_fmac_f32_e32 v125, v193, v193
	v_add_f32_e32 v124, v124, v125
	v_mul_f32_e32 v125, v187, v187
	v_fmac_f32_e32 v125, v131, v131
	v_add_f32_e32 v124, v125, v124
	v_mul_f32_e32 v125, v189, v189
	v_fmac_f32_e32 v125, v188, v188
	v_add_f32_e32 v124, v125, v124
	v_lshlrev_b32_e32 v125, 16, v152
	v_fmac_f32_e32 v125, 0.5, v116
	v_and_b32_e32 v116, 0xffff0000, v152
	v_fmac_f32_e32 v116, 0.5, v117
	v_lshlrev_b32_e32 v117, 16, v153
	v_fmac_f32_e32 v117, 0.5, v118
	v_and_b32_e32 v118, 0xffff0000, v153
	v_fmac_f32_e32 v118, 0.5, v119
	v_lshlrev_b32_e32 v119, 16, v154
	v_and_b32_e32 v126, 0xffff0000, v154
	v_fmac_f32_e32 v119, 0.5, v112
	v_fmac_f32_e32 v126, 0.5, v113
	v_lshlrev_b32_e32 v127, 16, v155
	v_and_b32_e32 v130, 0xffff0000, v155
	v_cvt_pk_bf16_f32 v112, v125, v116
	v_cvt_pk_bf16_f32 v113, v117, v118
	v_fmac_f32_e32 v127, 0.5, v114
	v_fmac_f32_e32 v130, 0.5, v115
	v_cvt_pk_bf16_f32 v114, v119, v126
	v_cvt_pk_bf16_f32 v115, v127, v130
	global_store_dwordx4 v[128:129], v[112:115], off offset:256
	s_nop 1
	v_mul_f32_e32 v112, v116, v116
	v_mul_f32_e32 v113, v118, v118
	v_fmac_f32_e32 v112, v125, v125
	v_fmac_f32_e32 v113, v117, v117
	v_add_f32_e32 v112, v112, v113
	v_mul_f32_e32 v113, v126, v126
	v_fmac_f32_e32 v113, v119, v119
	v_add_f32_e32 v112, v113, v112
	v_mul_f32_e32 v113, v130, v130
	v_fmac_f32_e32 v113, v127, v127
	v_add_f32_e32 v112, v113, v112
	v_add_f32_e32 v112, v124, v112
	v_mov_b32_e32 v113, v112
	s_nop 1
	v_permlane16_swap_b32_e32 v113, v112
	s_waitcnt lgkmcnt(0)
	v_add_f32_e32 v112, v112, v113
	v_mov_b32_e32 v113, v112
	s_nop 1
	v_permlane32_swap_b32_e32 v113, v112
	s_and_saveexec_b64 s[54:55], s[38:39]
	s_cbranch_execz .LBB0_1758
	s_add_u32 s58, s71, s57
	s_addc_u32 s59, s72, s56
	s_waitcnt lgkmcnt(0)
	v_add_f32_e32 v114, v112, v113
	v_lshl_add_u64 v[112:113], v[166:167], 2, s[58:59]
	global_store_dword v[112:113], v114, off
.LBB0_1758:
	s_or_b64 exec, exec, s[54:55]
	v_lshlrev_b32_e32 v114, 16, v148
	v_fmac_f32_e32 v114, 0.5, v108
	v_and_b32_e32 v108, 0xffff0000, v148
	v_fmac_f32_e32 v108, 0.5, v109
	v_lshlrev_b32_e32 v109, 16, v149
	v_fmac_f32_e32 v109, 0.5, v110
	v_and_b32_e32 v110, 0xffff0000, v149
	v_fmac_f32_e32 v110, 0.5, v111
	v_lshlrev_b32_e32 v111, 16, v150
	v_and_b32_e32 v115, 0xffff0000, v150
	v_fmac_f32_e32 v111, 0.5, v104
	v_fmac_f32_e32 v115, 0.5, v105
	v_cvt_pk_bf16_f32 v104, v114, v108
	v_cvt_pk_bf16_f32 v105, v109, v110
	v_mul_f32_e32 v108, v108, v108
	v_mul_f32_e32 v110, v110, v110
	v_and_b32_e32 v117, 0xffff0000, v151
	v_fmac_f32_e32 v108, v114, v114
	v_fmac_f32_e32 v110, v109, v109
	v_mul_f32_e32 v109, v115, v115
	v_lshlrev_b32_e32 v116, 16, v151
	v_fmac_f32_e32 v117, 0.5, v107
	v_add_f32_e32 v108, v108, v110
	v_fmac_f32_e32 v109, v111, v111
	v_fmac_f32_e32 v116, 0.5, v106
	v_add_f32_e32 v108, v109, v108
	v_mul_f32_e32 v109, v117, v117
	v_fmac_f32_e32 v109, v116, v116
	v_add_f32_e32 v108, v109, v108
	v_lshlrev_b32_e32 v109, 16, v144
	v_fmac_f32_e32 v109, 0.5, v100
	v_and_b32_e32 v100, 0xffff0000, v144
	v_and_b32_e32 v110, 0xffff0000, v145
	v_cvt_pk_bf16_f32 v106, v111, v115
	v_fmac_f32_e32 v100, 0.5, v101
	v_lshlrev_b32_e32 v101, 16, v145
	v_fmac_f32_e32 v110, 0.5, v103
	v_lshlrev_b32_e32 v111, 16, v146
	v_and_b32_e32 v114, 0xffff0000, v146
	v_fmac_f32_e32 v101, 0.5, v102
	v_fmac_f32_e32 v111, 0.5, v96
	v_fmac_f32_e32 v114, 0.5, v97
	v_mul_f32_e32 v96, v100, v100
	v_mul_f32_e32 v97, v110, v110
	v_fmac_f32_e32 v96, v109, v109
	v_fmac_f32_e32 v97, v101, v101
	v_cvt_pk_bf16_f32 v107, v116, v117
	v_and_b32_e32 v116, 0xffff0000, v147
	v_add_f32_e32 v96, v96, v97
	v_mul_f32_e32 v97, v114, v114
	v_lshlrev_b32_e32 v115, 16, v147
	v_fmac_f32_e32 v116, 0.5, v99
	v_fmac_f32_e32 v97, v111, v111
	v_fmac_f32_e32 v115, 0.5, v98
	v_add_f32_e32 v96, v97, v96
	v_mul_f32_e32 v97, v116, v116
	v_fmac_f32_e32 v97, v115, v115
	v_add_f32_e32 v96, v97, v96
	v_add_f32_e32 v99, v108, v96
	v_mov_b32_e32 v108, v99
	s_nop 1
	v_permlane16_swap_b32_e32 v108, v99
	s_waitcnt lgkmcnt(0)
	v_lshlrev_b64 v[112:113], 11, v[178:179]
	v_lshl_add_u64 v[96:97], v[112:113], 1, s[48:49]
	v_lshl_add_u64 v[102:103], v[168:169], 1, v[96:97]
	global_store_dwordx4 v[102:103], v[104:107], off
	s_waitcnt lgkmcnt(0)
	v_add_f32_e32 v96, v99, v108
	v_mov_b32_e32 v97, v96
	s_nop 1
	v_permlane32_swap_b32_e32 v97, v96
	v_cvt_pk_bf16_f32 v98, v109, v100
	v_cvt_pk_bf16_f32 v99, v101, v110
	v_cvt_pk_bf16_f32 v100, v111, v114
	v_cvt_pk_bf16_f32 v101, v115, v116
	global_store_dwordx4 v[102:103], v[98:101], off offset:256
	s_and_saveexec_b64 s[54:55], s[38:39]
	s_cbranch_execz .LBB0_1760
; __device__ __forceinline__ unsigned cvt_pk_bf16(float lo, float hi) { unsigned r; asm volatile("v_cvt_pk_bf16_f32 %0, %1, %2" : "=v"(r) : "v"(lo), "v"(hi)); return r; }
; __device__ __forceinline__ float xlane_add(float v, int lane_, int mask) { return v + __uint_as_float((unsigned)__builtin_amdgcn_ds_bpermute((lane_ ^ mask) << 2, (int)__float_as_uint(v))); }
;     __device__ __forceinline__ void operator()(const f32x4 (&acc)[2][2][4][2], const Unit& u, int wr, int wc, int fr, int fq) const {
;     ...
;             for (int m = 0; m < 4; ++m) { float ss = 0.f; const int row = row0 + ai * HALF + m * 16;
; #pragma unroll
;                 for (int bj = 0; bj < 2; ++bj) { const u32x4 xw = xa[m][bj]; const f32x4 a0 = acc[ai][bj][m][0], a1 = acc[ai][bj][m][1];
;                     const float v0 = __uint_as_float(xw.x << 16) + a0[0] * alpha, v1 = __uint_as_float(xw.x & 0xffff0000u) + a0[1] * alpha, v2 = __uint_as_float(xw.y << 16) + a0[2] * alpha, v3 = __uint_as_float(xw.y & 0xffff0000u) + a0[3] * alpha;
;                     const float v4 = __uint_as_float(xw.z << 16) + a1[0] * alpha, v5 = __uint_as_float(xw.z & 0xffff0000u) + a1[1] * alpha, v6 = __uint_as_float(xw.w << 16) + a1[2] * alpha, v7 = __uint_as_float(xw.w & 0xffff0000u) + a1[3] * alpha;
;                     u32x4 w; w.x = cvt_pk_bf16(v0, v1); w.y = cvt_pk_bf16(v2, v3); w.z = cvt_pk_bf16(v4, v5); w.w = cvt_pk_bf16(v6, v7);
;                     *(__attribute__((address_space(1))) u32x4*)(D + (size_t)row * ldx + col0 + bj * HALF) = w;
;                     ss += (v0 * v0 + v1 * v1) + (v2 * v2 + v3 * v3) + (v4 * v4 + v5 * v5) + (v6 * v6 + v7 * v7); }
;                 ss = xlane_add(ss, lane_, 16); ss = xlane_add(ss, lane_, 32);
;                 if (fq == 0) ((__attribute__((address_space(1))) float*)ssq)[(size_t)slot * mrows + row] = ss; }
	s_add_u32 s58, s71, s57
	s_addc_u32 s59, s72, s56
	s_waitcnt lgkmcnt(0)
	v_add_f32_e32 v98, v96, v97
	v_lshl_add_u64 v[96:97], v[166:167], 2, s[58:59]
	global_store_dword v[96:97], v98, off offset:64
.LBB0_1760:
	s_or_b64 exec, exec, s[54:55]
	v_lshlrev_b32_e32 v98, 16, v140
	v_fmac_f32_e32 v98, 0.5, v92
	v_and_b32_e32 v92, 0xffff0000, v140
	v_fmac_f32_e32 v92, 0.5, v93
	v_lshlrev_b32_e32 v93, 16, v141
	v_fmac_f32_e32 v93, 0.5, v94
	v_and_b32_e32 v94, 0xffff0000, v141
	v_fmac_f32_e32 v94, 0.5, v95
	v_lshlrev_b32_e32 v95, 16, v142
	v_and_b32_e32 v99, 0xffff0000, v142
	v_fmac_f32_e32 v95, 0.5, v88
	v_fmac_f32_e32 v99, 0.5, v89
	v_cvt_pk_bf16_f32 v88, v98, v92
	v_cvt_pk_bf16_f32 v89, v93, v94
	v_mul_f32_e32 v92, v92, v92
	v_mul_f32_e32 v94, v94, v94
	v_and_b32_e32 v101, 0xffff0000, v143
	v_fmac_f32_e32 v92, v98, v98
	v_fmac_f32_e32 v94, v93, v93
	v_mul_f32_e32 v93, v99, v99
	v_lshlrev_b32_e32 v100, 16, v143
	v_fmac_f32_e32 v101, 0.5, v91
	v_add_f32_e32 v92, v92, v94
	v_fmac_f32_e32 v93, v95, v95
	v_fmac_f32_e32 v100, 0.5, v90
	v_add_f32_e32 v92, v93, v92
	v_mul_f32_e32 v93, v101, v101
	v_fmac_f32_e32 v93, v100, v100
	v_add_f32_e32 v92, v93, v92
	v_lshlrev_b32_e32 v93, 16, v136
	v_fmac_f32_e32 v93, 0.5, v84
	v_and_b32_e32 v84, 0xffff0000, v136
	v_and_b32_e32 v94, 0xffff0000, v137
	v_cvt_pk_bf16_f32 v90, v95, v99
	v_fmac_f32_e32 v84, 0.5, v85
	v_lshlrev_b32_e32 v85, 16, v137
	v_fmac_f32_e32 v94, 0.5, v87
	v_lshlrev_b32_e32 v95, 16, v138
	v_and_b32_e32 v98, 0xffff0000, v138
	v_fmac_f32_e32 v85, 0.5, v86
	v_fmac_f32_e32 v95, 0.5, v80
	v_fmac_f32_e32 v98, 0.5, v81
	v_mul_f32_e32 v80, v84, v84
	v_mul_f32_e32 v81, v94, v94
	v_fmac_f32_e32 v80, v93, v93
	v_fmac_f32_e32 v81, v85, v85
	v_cvt_pk_bf16_f32 v91, v100, v101
	v_and_b32_e32 v100, 0xffff0000, v139
	v_add_f32_e32 v80, v80, v81
	v_mul_f32_e32 v81, v98, v98
	v_lshlrev_b32_e32 v99, 16, v139
	v_fmac_f32_e32 v100, 0.5, v83
	v_fmac_f32_e32 v81, v95, v95
	v_fmac_f32_e32 v99, 0.5, v82
	v_add_f32_e32 v80, v81, v80
	v_mul_f32_e32 v81, v100, v100
	v_fmac_f32_e32 v81, v99, v99
	v_add_f32_e32 v80, v81, v80
	v_add_f32_e32 v83, v92, v80
	v_mov_b32_e32 v92, v83
	s_nop 1
	v_permlane16_swap_b32_e32 v92, v83
	s_waitcnt lgkmcnt(0)
	v_lshlrev_b64 v[96:97], 11, v[176:177]
	v_lshl_add_u64 v[80:81], v[96:97], 1, s[48:49]
	v_lshl_add_u64 v[86:87], v[168:169], 1, v[80:81]
	global_store_dwordx4 v[86:87], v[88:91], off
	s_waitcnt lgkmcnt(0)
	v_add_f32_e32 v80, v83, v92
	v_mov_b32_e32 v81, v80
	s_nop 1
	v_permlane32_swap_b32_e32 v81, v80
	v_cvt_pk_bf16_f32 v82, v93, v84
	v_cvt_pk_bf16_f32 v83, v85, v94
	v_cvt_pk_bf16_f32 v84, v95, v98
	v_cvt_pk_bf16_f32 v85, v99, v100
	global_store_dwordx4 v[86:87], v[82:85], off offset:256
	s_and_saveexec_b64 s[54:55], s[38:39]
	s_cbranch_execz .LBB0_1762
	s_add_u32 s58, s71, s57
	s_addc_u32 s59, s72, s56
	s_waitcnt lgkmcnt(0)
	v_add_f32_e32 v82, v80, v81
	v_lshl_add_u64 v[80:81], v[166:167], 2, s[58:59]
	global_store_dword v[80:81], v82, off offset:128
.LBB0_1762:
	s_or_b64 exec, exec, s[54:55]
	v_lshlrev_b32_e32 v82, 16, v132
	v_fmac_f32_e32 v82, 0.5, v76
	v_and_b32_e32 v76, 0xffff0000, v132
	v_fmac_f32_e32 v76, 0.5, v77
	v_lshlrev_b32_e32 v77, 16, v133
	v_fmac_f32_e32 v77, 0.5, v78
	v_and_b32_e32 v78, 0xffff0000, v133
	v_fmac_f32_e32 v78, 0.5, v79
	v_lshlrev_b32_e32 v79, 16, v134
	v_and_b32_e32 v83, 0xffff0000, v134
	v_fmac_f32_e32 v79, 0.5, v72
	v_fmac_f32_e32 v83, 0.5, v73
	v_cvt_pk_bf16_f32 v72, v82, v76
	v_cvt_pk_bf16_f32 v73, v77, v78
	v_mul_f32_e32 v76, v76, v76
	v_mul_f32_e32 v78, v78, v78
	v_and_b32_e32 v85, 0xffff0000, v135
	v_fmac_f32_e32 v76, v82, v82
	v_fmac_f32_e32 v78, v77, v77
	v_mul_f32_e32 v77, v83, v83
	v_lshlrev_b32_e32 v84, 16, v135
	v_fmac_f32_e32 v85, 0.5, v75
	v_add_f32_e32 v76, v76, v78
	v_fmac_f32_e32 v77, v79, v79
	v_fmac_f32_e32 v84, 0.5, v74
	v_add_f32_e32 v76, v77, v76
	v_mul_f32_e32 v77, v85, v85
	v_fmac_f32_e32 v77, v84, v84
	v_add_f32_e32 v76, v77, v76
	v_lshlrev_b32_e32 v77, 16, v120
	v_fmac_f32_e32 v77, 0.5, v68
	v_and_b32_e32 v68, 0xffff0000, v120
	v_and_b32_e32 v78, 0xffff0000, v121
	v_cvt_pk_bf16_f32 v74, v79, v83
	v_fmac_f32_e32 v68, 0.5, v69
	v_lshlrev_b32_e32 v69, 16, v121
	v_fmac_f32_e32 v78, 0.5, v71
	v_lshlrev_b32_e32 v79, 16, v122
	v_and_b32_e32 v82, 0xffff0000, v122
	v_fmac_f32_e32 v69, 0.5, v70
	v_fmac_f32_e32 v79, 0.5, v64
	v_fmac_f32_e32 v82, 0.5, v65
	v_mul_f32_e32 v64, v68, v68
	v_mul_f32_e32 v65, v78, v78
	v_fmac_f32_e32 v64, v77, v77
	v_fmac_f32_e32 v65, v69, v69
	v_cvt_pk_bf16_f32 v75, v84, v85
	v_and_b32_e32 v84, 0xffff0000, v123
	v_add_f32_e32 v64, v64, v65
	v_mul_f32_e32 v65, v82, v82
	v_lshlrev_b32_e32 v83, 16, v123
	v_fmac_f32_e32 v84, 0.5, v67
	v_fmac_f32_e32 v65, v79, v79
	v_fmac_f32_e32 v83, 0.5, v66
	v_add_f32_e32 v64, v65, v64
	v_mul_f32_e32 v65, v84, v84
	v_fmac_f32_e32 v65, v83, v83
	v_add_f32_e32 v64, v65, v64
	v_add_f32_e32 v67, v76, v64
	v_mov_b32_e32 v76, v67
	s_nop 1
	v_permlane16_swap_b32_e32 v76, v67
	s_waitcnt lgkmcnt(0)
	v_lshlrev_b64 v[80:81], 11, v[174:175]
	v_lshl_add_u64 v[64:65], v[80:81], 1, s[48:49]
	v_lshl_add_u64 v[70:71], v[168:169], 1, v[64:65]
	global_store_dwordx4 v[70:71], v[72:75], off
	s_waitcnt lgkmcnt(0)
	v_add_f32_e32 v64, v67, v76
	v_mov_b32_e32 v65, v64
	s_nop 1
	v_permlane32_swap_b32_e32 v65, v64
	v_cvt_pk_bf16_f32 v66, v77, v68
	v_cvt_pk_bf16_f32 v67, v69, v78
	v_cvt_pk_bf16_f32 v68, v79, v82
	v_cvt_pk_bf16_f32 v69, v83, v84
	global_store_dwordx4 v[70:71], v[66:69], off offset:256
	s_and_saveexec_b64 s[54:55], s[38:39]
	s_cbranch_execz .LBB0_1764
	s_add_u32 s58, s71, s57
	s_addc_u32 s59, s72, s56
	s_waitcnt lgkmcnt(0)
	v_add_f32_e32 v66, v64, v65
	v_lshl_add_u64 v[64:65], v[166:167], 2, s[58:59]
	global_store_dword v[64:65], v66, off offset:192
; __device__ __forceinline__ unsigned cvt_pk_bf16(float lo, float hi) { unsigned r; asm volatile("v_cvt_pk_bf16_f32 %0, %1, %2" : "=v"(r) : "v"(lo), "v"(hi)); return r; }
; __device__ __forceinline__ float xlane_add(float v, int lane_, int mask) { return v + __uint_as_float((unsigned)__builtin_amdgcn_ds_bpermute((lane_ ^ mask) << 2, (int)__float_as_uint(v))); }
;     __device__ __forceinline__ void operator()(const f32x4 (&acc)[2][2][4][2], const Unit& u, int wr, int wc, int fr, int fq) const {
;     ...
;         for (int ai = 0; ai < 2; ++ai) { u32x4 xa[4][2];
; #pragma unroll
;             for (int m = 0; m < 4; ++m)
; #pragma unroll
;                 for (int bj = 0; bj < 2; ++bj) xa[m][bj] = *(const __attribute__((address_space(1))) u32x4*)(S + (size_t)(row0 + ai * HALF + m * 16) * ldx + col0 + bj * HALF);
; #pragma unroll
;             for (int m = 0; m < 4; ++m) { float ss = 0.f; const int row = row0 + ai * HALF + m * 16;
; #pragma unroll
;                 for (int bj = 0; bj < 2; ++bj) { const u32x4 xw = xa[m][bj]; const f32x4 a0 = acc[ai][bj][m][0], a1 = acc[ai][bj][m][1];
;                     const float v0 = __uint_as_float(xw.x << 16) + a0[0] * alpha, v1 = __uint_as_float(xw.x & 0xffff0000u) + a0[1] * alpha, v2 = __uint_as_float(xw.y << 16) + a0[2] * alpha, v3 = __uint_as_float(xw.y & 0xffff0000u) + a0[3] * alpha;
;                     const float v4 = __uint_as_float(xw.z << 16) + a1[0] * alpha, v5 = __uint_as_float(xw.z & 0xffff0000u) + a1[1] * alpha, v6 = __uint_as_float(xw.w << 16) + a1[2] * alpha, v7 = __uint_as_float(xw.w & 0xffff0000u) + a1[3] * alpha;
;                     u32x4 w; w.x = cvt_pk_bf16(v0, v1); w.y = cvt_pk_bf16(v2, v3); w.z = cvt_pk_bf16(v4, v5); w.w = cvt_pk_bf16(v6, v7);
;                     *(__attribute__((address_space(1))) u32x4*)(D + (size_t)row * ldx + col0 + bj * HALF) = w;
;                     ss += (v0 * v0 + v1 * v1) + (v2 * v2 + v3 * v3) + (v4 * v4 + v5 * v5) + (v6 * v6 + v7 * v7); }
;                 ss = xlane_add(ss, lane_, 16); ss = xlane_add(ss, lane_, 32);
;                 if (fq == 0) ((__attribute__((address_space(1))) float*)ssq)[(size_t)slot * mrows + row] = ss; }
.LBB0_1764:
	s_or_b64 exec, exec, s[54:55]
	s_mov_b64 s[54:55], 0x80000
	v_lshl_add_u64 v[102:103], v[172:173], 0, s[54:55]
	s_waitcnt lgkmcnt(0)
	v_lshl_add_u64 v[64:65], v[170:171], 0, v[102:103]
	global_load_dwordx4 v[98:101], v[64:65], off
	global_load_dwordx4 v[88:91], v[64:65], off offset:256
	v_add_u32_e32 v96, 0x90, v166
	v_ashrrev_i32_e32 v97, 31, v96
	v_lshlrev_b64 v[64:65], 12, v[96:97]
	v_add_u32_e32 v94, 0xa0, v166
	v_lshl_add_u64 v[64:65], v[170:171], 0, v[64:65]
	v_ashrrev_i32_e32 v95, 31, v94
	global_load_dwordx4 v[84:87], v[64:65], off
	global_load_dwordx4 v[80:83], v[64:65], off offset:256
	v_lshlrev_b64 v[64:65], 12, v[94:95]
	v_add_u32_e32 v92, 0xb0, v166
	v_lshl_add_u64 v[64:65], v[170:171], 0, v[64:65]
	v_ashrrev_i32_e32 v93, 31, v92
	global_load_dwordx4 v[76:79], v[64:65], off
	global_load_dwordx4 v[72:75], v[64:65], off offset:256
	v_lshlrev_b64 v[64:65], 12, v[92:93]
	v_lshl_add_u64 v[64:65], v[170:171], 0, v[64:65]
	global_load_dwordx4 v[68:71], v[64:65], off
	s_nop 0
	global_load_dwordx4 v[64:67], v[64:65], off offset:256
	s_waitcnt vmcnt(7)
	v_lshlrev_b32_e32 v105, 16, v99
	v_lshlrev_b32_e32 v104, 16, v98
	v_and_b32_e32 v98, 0xffff0000, v98
	v_fmac_f32_e32 v105, 0.5, v62
	v_and_b32_e32 v62, 0xffff0000, v99
	v_fmac_f32_e32 v104, 0.5, v60
	v_fmac_f32_e32 v98, 0.5, v61
	v_fmac_f32_e32 v62, 0.5, v63
	v_lshlrev_b32_e32 v63, 16, v100
	v_and_b32_e32 v99, 0xffff0000, v100
	v_lshl_add_u64 v[60:61], s[48:49], 0, v[102:103]
	v_fmac_f32_e32 v63, 0.5, v56
	v_fmac_f32_e32 v99, 0.5, v57
	v_lshlrev_b32_e32 v100, 16, v101
	v_and_b32_e32 v101, 0xffff0000, v101
	v_cvt_pk_bf16_f32 v56, v104, v98
	v_cvt_pk_bf16_f32 v57, v105, v62
	v_lshl_add_u64 v[60:61], v[168:169], 1, v[60:61]
	v_fmac_f32_e32 v100, 0.5, v58
	v_fmac_f32_e32 v101, 0.5, v59
	v_cvt_pk_bf16_f32 v58, v63, v99
	v_cvt_pk_bf16_f32 v59, v100, v101
	global_store_dwordx4 v[60:61], v[56:59], off
	s_nop 1
	v_mul_f32_e32 v56, v98, v98
	v_mul_f32_e32 v57, v62, v62
	v_fmac_f32_e32 v56, v104, v104
	v_fmac_f32_e32 v57, v105, v105
	v_add_f32_e32 v56, v56, v57
	v_mul_f32_e32 v57, v99, v99
	v_fmac_f32_e32 v57, v63, v63
	v_add_f32_e32 v56, v57, v56
	v_mul_f32_e32 v57, v101, v101
	v_fmac_f32_e32 v57, v100, v100
	v_add_f32_e32 v56, v57, v56
	s_waitcnt vmcnt(7)
	v_lshlrev_b32_e32 v57, 16, v88
	v_fmac_f32_e32 v57, 0.5, v52
	v_and_b32_e32 v52, 0xffff0000, v88
	v_fmac_f32_e32 v52, 0.5, v53
	v_lshlrev_b32_e32 v53, 16, v89
	v_fmac_f32_e32 v53, 0.5, v54
	v_and_b32_e32 v54, 0xffff0000, v89
	v_fmac_f32_e32 v54, 0.5, v55
	v_lshlrev_b32_e32 v55, 16, v90
	v_and_b32_e32 v58, 0xffff0000, v90
	v_fmac_f32_e32 v55, 0.5, v48
	v_fmac_f32_e32 v58, 0.5, v49
	v_lshlrev_b32_e32 v59, 16, v91
	v_and_b32_e32 v62, 0xffff0000, v91
	v_cvt_pk_bf16_f32 v48, v57, v52
	v_cvt_pk_bf16_f32 v49, v53, v54
	v_fmac_f32_e32 v59, 0.5, v50
	v_fmac_f32_e32 v62, 0.5, v51
	v_cvt_pk_bf16_f32 v50, v55, v58
	v_cvt_pk_bf16_f32 v51, v59, v62
	global_store_dwordx4 v[60:61], v[48:51], off offset:256
	s_nop 1
	v_mul_f32_e32 v48, v52, v52
	v_mul_f32_e32 v49, v54, v54
	v_fmac_f32_e32 v48, v57, v57
	v_fmac_f32_e32 v49, v53, v53
	v_add_f32_e32 v48, v48, v49
	v_mul_f32_e32 v49, v58, v58
	v_fmac_f32_e32 v49, v55, v55
	v_add_f32_e32 v48, v49, v48
	v_mul_f32_e32 v49, v62, v62
	v_fmac_f32_e32 v49, v59, v59
	v_add_f32_e32 v48, v49, v48
	v_add_f32_e32 v48, v56, v48
	v_mov_b32_e32 v49, v48
	s_nop 1
	v_permlane16_swap_b32_e32 v49, v48
	s_waitcnt lgkmcnt(0)
	v_add_f32_e32 v48, v48, v49
	v_mov_b32_e32 v49, v48
	s_nop 1
	v_permlane32_swap_b32_e32 v49, v48
	s_and_saveexec_b64 s[54:55], s[38:39]
	s_cbranch_execz .LBB0_1766
	s_add_u32 s58, s71, s57
	s_addc_u32 s59, s72, s56
	s_waitcnt lgkmcnt(0)
	v_add_f32_e32 v50, v48, v49
	v_lshl_add_u64 v[48:49], v[166:167], 2, s[58:59]
	global_store_dword v[48:49], v50, off offset:512
.LBB0_1766:
	s_or_b64 exec, exec, s[54:55]
	s_waitcnt vmcnt(7)
	v_lshlrev_b32_e32 v50, 16, v84
	v_fmac_f32_e32 v50, 0.5, v44
	v_and_b32_e32 v44, 0xffff0000, v84
	v_fmac_f32_e32 v44, 0.5, v45
	v_lshlrev_b32_e32 v45, 16, v85
	v_fmac_f32_e32 v45, 0.5, v46
	v_and_b32_e32 v46, 0xffff0000, v85
	v_fmac_f32_e32 v46, 0.5, v47
	v_lshlrev_b32_e32 v47, 16, v86
	v_and_b32_e32 v51, 0xffff0000, v86
	v_fmac_f32_e32 v47, 0.5, v40
	v_fmac_f32_e32 v51, 0.5, v41
	v_cvt_pk_bf16_f32 v40, v50, v44
	v_cvt_pk_bf16_f32 v41, v45, v46
	v_mul_f32_e32 v44, v44, v44
	v_mul_f32_e32 v46, v46, v46
	v_and_b32_e32 v53, 0xffff0000, v87
	v_fmac_f32_e32 v44, v50, v50
	v_fmac_f32_e32 v46, v45, v45
	v_mul_f32_e32 v45, v51, v51
	v_lshlrev_b32_e32 v52, 16, v87
	v_fmac_f32_e32 v53, 0.5, v43
	v_add_f32_e32 v44, v44, v46
	v_fmac_f32_e32 v45, v47, v47
	v_fmac_f32_e32 v52, 0.5, v42
	v_add_f32_e32 v44, v45, v44
	v_mul_f32_e32 v45, v53, v53
	v_fmac_f32_e32 v45, v52, v52
	v_add_f32_e32 v44, v45, v44
	s_waitcnt vmcnt(6)
	v_lshlrev_b32_e32 v45, 16, v80
	v_fmac_f32_e32 v45, 0.5, v36
	v_and_b32_e32 v36, 0xffff0000, v80
	v_and_b32_e32 v46, 0xffff0000, v81
	v_cvt_pk_bf16_f32 v42, v47, v51
	v_fmac_f32_e32 v36, 0.5, v37
	v_lshlrev_b32_e32 v37, 16, v81
	v_fmac_f32_e32 v46, 0.5, v39
	v_lshlrev_b32_e32 v47, 16, v82
	v_and_b32_e32 v50, 0xffff0000, v82
	v_fmac_f32_e32 v37, 0.5, v38
	v_fmac_f32_e32 v47, 0.5, v32
	v_fmac_f32_e32 v50, 0.5, v33
	v_mul_f32_e32 v32, v36, v36
	v_mul_f32_e32 v33, v46, v46
	v_fmac_f32_e32 v32, v45, v45
	v_fmac_f32_e32 v33, v37, v37
	v_cvt_pk_bf16_f32 v43, v52, v53
	v_and_b32_e32 v52, 0xffff0000, v83
	v_add_f32_e32 v32, v32, v33
	v_mul_f32_e32 v33, v50, v50
	v_lshlrev_b32_e32 v51, 16, v83
	v_fmac_f32_e32 v52, 0.5, v35
	v_fmac_f32_e32 v33, v47, v47
	v_fmac_f32_e32 v51, 0.5, v34
	v_add_f32_e32 v32, v33, v32
	v_mul_f32_e32 v33, v52, v52
	v_fmac_f32_e32 v33, v51, v51
	v_add_f32_e32 v32, v33, v32
	v_add_f32_e32 v35, v44, v32
	v_mov_b32_e32 v44, v35
	s_nop 1
	v_permlane16_swap_b32_e32 v44, v35
	s_waitcnt lgkmcnt(0)
	v_lshlrev_b64 v[48:49], 11, v[96:97]
	v_lshl_add_u64 v[32:33], v[48:49], 1, s[48:49]
	v_lshl_add_u64 v[38:39], v[168:169], 1, v[32:33]
	global_store_dwordx4 v[38:39], v[40:43], off
	s_waitcnt lgkmcnt(0)
	v_add_f32_e32 v32, v35, v44
	v_mov_b32_e32 v33, v32
	s_nop 1
	v_permlane32_swap_b32_e32 v33, v32
	v_cvt_pk_bf16_f32 v34, v45, v36
	v_cvt_pk_bf16_f32 v35, v37, v46
	v_cvt_pk_bf16_f32 v36, v47, v50
	v_cvt_pk_bf16_f32 v37, v51, v52
	global_store_dwordx4 v[38:39], v[34:37], off offset:256
	s_and_saveexec_b64 s[54:55], s[38:39]
	s_cbranch_execz .LBB0_1768
	s_add_u32 s58, s71, s57
	s_addc_u32 s59, s72, s56
	s_waitcnt lgkmcnt(0)
	v_add_f32_e32 v34, v32, v33
	v_lshl_add_u64 v[32:33], v[166:167], 2, s[58:59]
	global_store_dword v[32:33], v34, off offset:576
; __device__ __forceinline__ unsigned cvt_pk_bf16(float lo, float hi) { unsigned r; asm volatile("v_cvt_pk_bf16_f32 %0, %1, %2" : "=v"(r) : "v"(lo), "v"(hi)); return r; }
; __device__ __forceinline__ float xlane_add(float v, int lane_, int mask) { return v + __uint_as_float((unsigned)__builtin_amdgcn_ds_bpermute((lane_ ^ mask) << 2, (int)__float_as_uint(v))); }
;     __device__ __forceinline__ void operator()(const f32x4 (&acc)[2][2][4][2], const Unit& u, int wr, int wc, int fr, int fq) const {
;     ...
;             for (int m = 0; m < 4; ++m) { float ss = 0.f; const int row = row0 + ai * HALF + m * 16;
; #pragma unroll
;                 for (int bj = 0; bj < 2; ++bj) { const u32x4 xw = xa[m][bj]; const f32x4 a0 = acc[ai][bj][m][0], a1 = acc[ai][bj][m][1];
;                     const float v0 = __uint_as_float(xw.x << 16) + a0[0] * alpha, v1 = __uint_as_float(xw.x & 0xffff0000u) + a0[1] * alpha, v2 = __uint_as_float(xw.y << 16) + a0[2] * alpha, v3 = __uint_as_float(xw.y & 0xffff0000u) + a0[3] * alpha;
;                     const float v4 = __uint_as_float(xw.z << 16) + a1[0] * alpha, v5 = __uint_as_float(xw.z & 0xffff0000u) + a1[1] * alpha, v6 = __uint_as_float(xw.w << 16) + a1[2] * alpha, v7 = __uint_as_float(xw.w & 0xffff0000u) + a1[3] * alpha;
;                     u32x4 w; w.x = cvt_pk_bf16(v0, v1); w.y = cvt_pk_bf16(v2, v3); w.z = cvt_pk_bf16(v4, v5); w.w = cvt_pk_bf16(v6, v7);
;                     *(__attribute__((address_space(1))) u32x4*)(D + (size_t)row * ldx + col0 + bj * HALF) = w;
;                     ss += (v0 * v0 + v1 * v1) + (v2 * v2 + v3 * v3) + (v4 * v4 + v5 * v5) + (v6 * v6 + v7 * v7); }
;                 ss = xlane_add(ss, lane_, 16); ss = xlane_add(ss, lane_, 32);
;                 if (fq == 0) ((__attribute__((address_space(1))) float*)ssq)[(size_t)slot * mrows + row] = ss; }
.LBB0_1768:
	s_or_b64 exec, exec, s[54:55]
	s_waitcnt vmcnt(7)
	v_lshlrev_b32_e32 v34, 16, v76
	v_fmac_f32_e32 v34, 0.5, v28
	v_and_b32_e32 v28, 0xffff0000, v76
	v_fmac_f32_e32 v28, 0.5, v29
	v_lshlrev_b32_e32 v29, 16, v77
	v_fmac_f32_e32 v29, 0.5, v30
	v_and_b32_e32 v30, 0xffff0000, v77
	v_fmac_f32_e32 v30, 0.5, v31
	v_lshlrev_b32_e32 v31, 16, v78
	v_and_b32_e32 v35, 0xffff0000, v78
	v_fmac_f32_e32 v31, 0.5, v24
	v_fmac_f32_e32 v35, 0.5, v25
	v_cvt_pk_bf16_f32 v24, v34, v28
	v_cvt_pk_bf16_f32 v25, v29, v30
	v_mul_f32_e32 v28, v28, v28
	v_mul_f32_e32 v30, v30, v30
	v_and_b32_e32 v37, 0xffff0000, v79
	v_fmac_f32_e32 v28, v34, v34
	v_fmac_f32_e32 v30, v29, v29
	v_mul_f32_e32 v29, v35, v35
	v_lshlrev_b32_e32 v36, 16, v79
	v_fmac_f32_e32 v37, 0.5, v27
	v_add_f32_e32 v28, v28, v30
	v_fmac_f32_e32 v29, v31, v31
	v_fmac_f32_e32 v36, 0.5, v26
	v_add_f32_e32 v28, v29, v28
	v_mul_f32_e32 v29, v37, v37
	v_fmac_f32_e32 v29, v36, v36
	v_add_f32_e32 v28, v29, v28
	s_waitcnt vmcnt(6)
	v_lshlrev_b32_e32 v29, 16, v72
	v_fmac_f32_e32 v29, 0.5, v20
	v_and_b32_e32 v20, 0xffff0000, v72
	v_and_b32_e32 v30, 0xffff0000, v73
	v_cvt_pk_bf16_f32 v26, v31, v35
	v_fmac_f32_e32 v20, 0.5, v21
	v_lshlrev_b32_e32 v21, 16, v73
	v_fmac_f32_e32 v30, 0.5, v23
	v_lshlrev_b32_e32 v31, 16, v74
	v_and_b32_e32 v34, 0xffff0000, v74
	v_fmac_f32_e32 v21, 0.5, v22
	v_fmac_f32_e32 v31, 0.5, v16
	v_fmac_f32_e32 v34, 0.5, v17
	v_mul_f32_e32 v16, v20, v20
	v_mul_f32_e32 v17, v30, v30
	v_fmac_f32_e32 v16, v29, v29
	v_fmac_f32_e32 v17, v21, v21
	v_cvt_pk_bf16_f32 v27, v36, v37
	v_and_b32_e32 v36, 0xffff0000, v75
	v_add_f32_e32 v16, v16, v17
	v_mul_f32_e32 v17, v34, v34
	v_lshlrev_b32_e32 v35, 16, v75
	v_fmac_f32_e32 v36, 0.5, v19
	v_fmac_f32_e32 v17, v31, v31
	v_fmac_f32_e32 v35, 0.5, v18
	v_add_f32_e32 v16, v17, v16
	v_mul_f32_e32 v17, v36, v36
	v_fmac_f32_e32 v17, v35, v35
	v_add_f32_e32 v16, v17, v16
	v_add_f32_e32 v19, v28, v16
	v_mov_b32_e32 v28, v19
	s_nop 1
	v_permlane16_swap_b32_e32 v28, v19
	s_waitcnt lgkmcnt(0)
	v_lshlrev_b64 v[32:33], 11, v[94:95]
	v_lshl_add_u64 v[16:17], v[32:33], 1, s[48:49]
	v_lshl_add_u64 v[22:23], v[168:169], 1, v[16:17]
	global_store_dwordx4 v[22:23], v[24:27], off
	s_waitcnt lgkmcnt(0)
	v_add_f32_e32 v16, v19, v28
	v_mov_b32_e32 v17, v16
	s_nop 1
	v_permlane32_swap_b32_e32 v17, v16
	v_cvt_pk_bf16_f32 v18, v29, v20
	v_cvt_pk_bf16_f32 v19, v21, v30
	v_cvt_pk_bf16_f32 v20, v31, v34
	v_cvt_pk_bf16_f32 v21, v35, v36
	global_store_dwordx4 v[22:23], v[18:21], off offset:256
	s_and_saveexec_b64 s[54:55], s[38:39]
	s_cbranch_execz .LBB0_1770
	s_add_u32 s58, s71, s57
	s_addc_u32 s59, s72, s56
	s_waitcnt lgkmcnt(0)
	v_add_f32_e32 v18, v16, v17
	v_lshl_add_u64 v[16:17], v[166:167], 2, s[58:59]
	global_store_dword v[16:17], v18, off offset:640
.LBB0_1770:
	s_or_b64 exec, exec, s[54:55]
	s_waitcnt vmcnt(7)
	v_lshlrev_b32_e32 v18, 16, v68
	v_fmac_f32_e32 v18, 0.5, v12
	v_and_b32_e32 v12, 0xffff0000, v68
	v_fmac_f32_e32 v12, 0.5, v13
	v_lshlrev_b32_e32 v13, 16, v69
	v_fmac_f32_e32 v13, 0.5, v14
	v_and_b32_e32 v14, 0xffff0000, v69
	v_fmac_f32_e32 v14, 0.5, v15
	v_lshlrev_b32_e32 v15, 16, v70
	v_and_b32_e32 v19, 0xffff0000, v70
	v_fmac_f32_e32 v15, 0.5, v8
	v_fmac_f32_e32 v19, 0.5, v9
	v_cvt_pk_bf16_f32 v8, v18, v12
	v_cvt_pk_bf16_f32 v9, v13, v14
	v_mul_f32_e32 v12, v12, v12
	v_mul_f32_e32 v14, v14, v14
	v_and_b32_e32 v21, 0xffff0000, v71
	v_fmac_f32_e32 v12, v18, v18
	v_fmac_f32_e32 v14, v13, v13
	v_mul_f32_e32 v13, v19, v19
	v_lshlrev_b32_e32 v20, 16, v71
	v_fmac_f32_e32 v21, 0.5, v11
	v_add_f32_e32 v12, v12, v14
	v_fmac_f32_e32 v13, v15, v15
	v_fmac_f32_e32 v20, 0.5, v10
	v_add_f32_e32 v12, v13, v12
	v_mul_f32_e32 v13, v21, v21
	v_fmac_f32_e32 v13, v20, v20
	v_add_f32_e32 v12, v13, v12
	s_waitcnt vmcnt(6)
	v_lshlrev_b32_e32 v13, 16, v64
	v_fmac_f32_e32 v13, 0.5, v4
	v_and_b32_e32 v4, 0xffff0000, v64
	v_and_b32_e32 v14, 0xffff0000, v65
	v_cvt_pk_bf16_f32 v10, v15, v19
	v_fmac_f32_e32 v4, 0.5, v5
	v_lshlrev_b32_e32 v5, 16, v65
	v_fmac_f32_e32 v14, 0.5, v7
	v_lshlrev_b32_e32 v15, 16, v66
	v_and_b32_e32 v18, 0xffff0000, v66
	v_fmac_f32_e32 v5, 0.5, v6
	v_fmac_f32_e32 v15, 0.5, v0
	v_fmac_f32_e32 v18, 0.5, v1
	v_mul_f32_e32 v0, v4, v4
	v_mul_f32_e32 v1, v14, v14
	v_fmac_f32_e32 v0, v13, v13
	v_fmac_f32_e32 v1, v5, v5
	v_cvt_pk_bf16_f32 v11, v20, v21
	v_and_b32_e32 v20, 0xffff0000, v67
	v_add_f32_e32 v0, v0, v1
	v_mul_f32_e32 v1, v18, v18
	v_lshlrev_b32_e32 v19, 16, v67
	v_fmac_f32_e32 v20, 0.5, v3
	v_fmac_f32_e32 v1, v15, v15
	v_fmac_f32_e32 v19, 0.5, v2
	v_add_f32_e32 v0, v1, v0
	v_mul_f32_e32 v1, v20, v20
	v_fmac_f32_e32 v1, v19, v19
	v_add_f32_e32 v0, v1, v0
	v_add_f32_e32 v3, v12, v0
	v_mov_b32_e32 v12, v3
	s_nop 1
	v_permlane16_swap_b32_e32 v12, v3
	s_waitcnt lgkmcnt(0)
	v_lshlrev_b64 v[16:17], 11, v[92:93]
	v_lshl_add_u64 v[0:1], v[16:17], 1, s[48:49]
	v_lshl_add_u64 v[6:7], v[168:169], 1, v[0:1]
	global_store_dwordx4 v[6:7], v[8:11], off
	s_waitcnt lgkmcnt(0)
	v_add_f32_e32 v0, v3, v12
	v_mov_b32_e32 v1, v0
	s_nop 1
	v_permlane32_swap_b32_e32 v1, v0
	v_cvt_pk_bf16_f32 v2, v13, v4
	v_cvt_pk_bf16_f32 v3, v5, v14
	v_cvt_pk_bf16_f32 v4, v15, v18
	v_cvt_pk_bf16_f32 v5, v19, v20
	global_store_dwordx4 v[6:7], v[2:5], off offset:256
	s_and_saveexec_b64 s[54:55], s[38:39]
	s_cbranch_execz .LBB0_1772
	s_add_u32 s58, s71, s57
	s_addc_u32 s59, s72, s56
	s_waitcnt lgkmcnt(0)
	v_add_f32_e32 v2, v0, v1
	v_lshl_add_u64 v[0:1], v[166:167], 2, s[58:59]
	global_store_dword v[0:1], v2, off offset:704

; __device__ __forceinline__ void grid_barrier_impl(int wave, unsigned G, unsigned xcc, volatile LAS unsigned* st) {
;     ...
;             st[0] = nloc; st[1] = nx;
.LBB0_1784:
	v_readlane_b32 s36, v255, 8
	s_nop 1
	v_mov_b32_e32 v2, s36
	v_readlane_b32 s36, v255, 9
	ds_write_b32 v2, v1
	s_nop 0
	v_mov_b32_e32 v2, s36
	s_waitcnt lgkmcnt(0)
	ds_write_b32 v2, v0
